# attention: counted lgkmcnt in PV, K-tile LDS writes moved before the B1 barrier, prio 1 for waves 4-7; P2 GEMM: DMA issue balanced 4/4/4/4 per load segment; P5 epilogue loads ahead
# speedup vs baseline: 1.0082x; 1.0082x over previous
; #define PG8_STAGE(bufoff, gbase, voff) do { _Pragma("unroll") for (int _i = 0; _i < 2; ++_i) \
;         __builtin_amdgcn_global_load_lds((const unsigned*)((const char*)(gbase) + (voff)[_i]), (PG8_LAS unsigned*)(lds + (bufoff) + ldsw + _i * 8192), 16, 0, 0); } while (0)
; #define PG8_LDA(dst, b, h) do { _Pragma("unroll") for (int m = 0; m < 4; ++m) _Pragma("unroll") for (int k = 0; k < 2; ++k) dst[m][k] = *(const PG8_LAS bf16x8*)(lds + PG8_SA(b, h) + aoff + m * 2048 + k * 1024); } while (0)
; #define PG8_LDB(dst, b, h) do { _Pragma("unroll") for (int n = 0; n < 2; ++n) _Pragma("unroll") for (int k = 0; k < 2; ++k) dst[n][k] = *(const PG8_LAS bf16x8*)(lds + PG8_SB(b, h) + boff + n * 2048 + k * 1024); } while (0)
; template <class Epi, class Sched, bool ALIGN_EPI = false, bool SP2 = false>
; __device__ __forceinline__ void gemm_phase(PG8_LAS unsigned char* lds, const Gemm g, const Sched& S, const Epi& E) {
;     ...
;         for (int t = 0; t < nt; t += 2) {
;             const bool last = (t == nt - 2);
;             const char* a1 = cA + (size_t)(t + 1) * kstep;
;             const char* a2 = last ? nA : cA + (size_t)(t + 2) * kstep; const char* b2 = last ? nB : cB + (size_t)(t + 2) * kstep;
;             const char* a3 = a2 + kstep; const char* b3 = b2 + kstep;
;             if (last && has_next) S.a_ready(nxt);
;             if constexpr (SP2) {
;             PG8_LDB(B0, 0, 0); PG8_LDB(B1, 0, 1); PG8_SCHED; PG8_LDA(At, 0, 0); PG8_STAGE(PG8_SA(1, 1), a1 + hstep, voffA);
;             PG8_WAIT_V(8); PG8_WAIT_L(0); PG8_BAR; PG8_MMA(0, 0, At, B0); PG8_MMA(0, 1, At, B1); PG8_BAR; PG8_SCHED;
;             PG8_LDA(At, 0, 1); PG8_STAGE(PG8_SB(0, 0), b2, voffB); PG8_STAGE(PG8_SB(0, 1), b2 + hstep, voffB); PG8_STAGE(PG8_SA(0, 0), a2, voffA);
;             PG8_WAIT_V(8); PG8_WAIT_L(0); PG8_BAR; PG8_MMA(1, 0, At, B0); PG8_MMA(1, 1, At, B1); PG8_BAR; PG8_SCHED;
;             PG8_LDB(B0, 1, 0); PG8_LDB(B1, 1, 1); PG8_SCHED; PG8_LDA(At, 1, 0); PG8_STAGE(PG8_SA(0, 1), a2 + hstep, voffA);
;             PG8_WAIT_V(8); PG8_WAIT_L(0); PG8_BAR; PG8_MMA(0, 0, At, B0); PG8_MMA(0, 1, At, B1); PG8_BAR; PG8_SCHED;
;             PG8_LDA(At, 1, 1); PG8_STAGE(PG8_SB(1, 0), b3, voffB); PG8_STAGE(PG8_SB(1, 1), b3 + hstep, voffB); PG8_STAGE(PG8_SA(1, 0), a3, voffA);
;             PG8_WAIT_V(8); PG8_WAIT_L(0); PG8_BAR; PG8_MMA(1, 0, At, B0); PG8_MMA(1, 1, At, B1); PG8_BAR; PG8_SCHED;
.LBB0_297:
	ds_read_b128 v[128:131], v170
	ds_read_b128 v[132:135], v170 offset:1024
	ds_read_b128 v[158:161], v170 offset:2048
	ds_read_b128 v[176:179], v170 offset:3072
	ds_read_b128 v[180:183], v171
	ds_read_b128 v[184:187], v171 offset:1024
	ds_read_b128 v[188:191], v171 offset:2048
	ds_read_b128 v[192:195], v171 offset:3072
	s_add_u32 s76, s36, 0xfff80000
	s_addc_u32 s77, s37, -1
	s_add_u32 s48, s36, 0xfff80080
	s_addc_u32 s49, s37, -1
	s_cmp_eq_u32 s75, 28
	s_cselect_b32 s53, s1, s49
	s_cselect_b32 s52, s5, s48
	s_cselect_b32 s49, s31, s74
	s_cselect_b32 s48, s33, s35
	v_lshl_add_u64 v[162:163], s[76:77], 0, v[150:151]
	s_mov_b32 m0, s60
	ds_read_b128 v[196:199], v172
	ds_read_b128 v[200:203], v172 offset:1024
	ds_read_b128 v[204:207], v172 offset:2048
	ds_read_b128 v[208:211], v172 offset:3072
	ds_read_b128 v[212:215], v172 offset:4096
	ds_read_b128 v[216:219], v172 offset:5120
	ds_read_b128 v[220:223], v172 offset:6144
	ds_read_b128 v[224:227], v172 offset:7168
	global_load_lds_dwordx4 v[162:163], off
	v_lshl_add_u64 v[162:163], s[76:77], 0, v[152:153]
	s_mov_b32 m0, s61
	s_nop 0
	global_load_lds_dwordx4 v[162:163], off
	v_lshl_add_u64 v[162:163], s[36:37], 0, v[150:151]
	s_add_i32 m0, s55, 0xc000
	s_nop 0
	global_load_lds_dwordx4 v[162:163], off
	v_lshl_add_u64 v[162:163], s[36:37], 0, v[152:153]
	s_add_i32 m0, s55, 0xe000
	s_nop 0
	global_load_lds_dwordx4 v[162:163], off
	s_waitcnt vmcnt(8)
	s_waitcnt lgkmcnt(0)
	s_barrier
	s_setprio 1
	s_waitcnt lgkmcnt(0)
	v_mfma_f32_16x16x32_bf16 v[124:127], v[128:131], v[196:199], v[124:127]
	v_mfma_f32_16x16x32_bf16 v[120:123], v[158:161], v[196:199], v[120:123]
	v_mfma_f32_16x16x32_bf16 v[108:111], v[128:131], v[204:207], v[108:111]
	v_mfma_f32_16x16x32_bf16 v[104:107], v[158:161], v[204:207], v[104:107]
	v_mfma_f32_16x16x32_bf16 v[92:95], v[128:131], v[212:215], v[92:95]
	v_mfma_f32_16x16x32_bf16 v[88:91], v[158:161], v[212:215], v[88:91]
	v_mfma_f32_16x16x32_bf16 v[76:79], v[128:131], v[220:223], v[76:79]
	v_mfma_f32_16x16x32_bf16 v[72:75], v[158:161], v[220:223], v[72:75]
	v_mfma_f32_16x16x32_bf16 v[124:127], v[132:135], v[200:203], v[124:127]
	v_mfma_f32_16x16x32_bf16 v[120:123], v[176:179], v[200:203], v[120:123]
	v_mfma_f32_16x16x32_bf16 v[108:111], v[132:135], v[208:211], v[108:111]
	v_mfma_f32_16x16x32_bf16 v[104:107], v[176:179], v[208:211], v[104:107]
	v_mfma_f32_16x16x32_bf16 v[92:95], v[132:135], v[216:219], v[92:95]
	v_mfma_f32_16x16x32_bf16 v[88:91], v[176:179], v[216:219], v[88:91]
	v_mfma_f32_16x16x32_bf16 v[76:79], v[132:135], v[224:227], v[76:79]
	v_mfma_f32_16x16x32_bf16 v[72:75], v[176:179], v[224:227], v[72:75]
	s_setprio 0
	s_setprio 1
	v_mfma_f32_16x16x32_bf16 v[116:119], v[180:183], v[196:199], v[116:119]
	v_mfma_f32_16x16x32_bf16 v[112:115], v[188:191], v[196:199], v[112:115]
	v_mfma_f32_16x16x32_bf16 v[100:103], v[180:183], v[204:207], v[100:103]
	v_mfma_f32_16x16x32_bf16 v[96:99], v[188:191], v[204:207], v[96:99]
	v_mfma_f32_16x16x32_bf16 v[84:87], v[180:183], v[212:215], v[84:87]
	v_mfma_f32_16x16x32_bf16 v[80:83], v[188:191], v[212:215], v[80:83]
	v_mfma_f32_16x16x32_bf16 v[68:71], v[180:183], v[220:223], v[68:71]
	v_mfma_f32_16x16x32_bf16 v[64:67], v[188:191], v[220:223], v[64:67]
	v_mfma_f32_16x16x32_bf16 v[116:119], v[184:187], v[200:203], v[116:119]
	v_mfma_f32_16x16x32_bf16 v[112:115], v[192:195], v[200:203], v[112:115]
	v_mfma_f32_16x16x32_bf16 v[100:103], v[184:187], v[208:211], v[100:103]
	v_mfma_f32_16x16x32_bf16 v[96:99], v[192:195], v[208:211], v[96:99]
	v_mfma_f32_16x16x32_bf16 v[84:87], v[184:187], v[216:219], v[84:87]
	v_mfma_f32_16x16x32_bf16 v[80:83], v[192:195], v[216:219], v[80:83]
	v_mfma_f32_16x16x32_bf16 v[68:71], v[184:187], v[224:227], v[68:71]
	v_mfma_f32_16x16x32_bf16 v[64:67], v[192:195], v[224:227], v[64:67]
	s_setprio 0
	s_barrier
	s_add_i32 s76, s66, s54
	v_lshl_add_u64 v[162:163], s[48:49], 0, v[138:139]
	s_mov_b32 m0, s76
	ds_read_b128 v[196:199], v172 offset:16384
	ds_read_b128 v[200:203], v172 offset:17408
	ds_read_b128 v[204:207], v172 offset:18432
	ds_read_b128 v[208:211], v172 offset:19456
	ds_read_b128 v[212:215], v172 offset:20480
	ds_read_b128 v[216:219], v172 offset:21504
	ds_read_b128 v[220:223], v172 offset:22528
	ds_read_b128 v[224:227], v172 offset:23552
	global_load_lds_dwordx4 v[162:163], off
	s_add_i32 m0, s76, 0x2000
	s_add_u32 s76, s48, 0x80000
	v_lshl_add_u64 v[228:229], s[48:49], 0, v[142:143]
	s_addc_u32 s77, s49, 0
	s_add_i32 s80, s67, s54
	global_load_lds_dwordx4 v[228:229], off
	v_lshl_add_u64 v[230:231], s[76:77], 0, v[138:139]
	s_mov_b32 m0, s80
	v_lshl_add_u64 v[232:233], s[52:53], 0, v[140:141]
	global_load_lds_dwordx4 v[230:231], off
	v_lshl_add_u64 v[230:231], s[76:77], 0, v[142:143]
	s_add_i32 m0, s80, 0x2000
	s_nop 0
	global_load_lds_dwordx4 v[230:231], off
	s_waitcnt vmcnt(6)
	s_waitcnt lgkmcnt(0)
	s_barrier
; #define PG8_STAGE(bufoff, gbase, voff) do { _Pragma("unroll") for (int _i = 0; _i < 2; ++_i) \
;         __builtin_amdgcn_global_load_lds((const unsigned*)((const char*)(gbase) + (voff)[_i]), (PG8_LAS unsigned*)(lds + (bufoff) + ldsw + _i * 8192), 16, 0, 0); } while (0)
; #define PG8_LDA(dst, b, h) do { _Pragma("unroll") for (int m = 0; m < 4; ++m) _Pragma("unroll") for (int k = 0; k < 2; ++k) dst[m][k] = *(const PG8_LAS bf16x8*)(lds + PG8_SA(b, h) + aoff + m * 2048 + k * 1024); } while (0)
; #define PG8_LDB(dst, b, h) do { _Pragma("unroll") for (int n = 0; n < 2; ++n) _Pragma("unroll") for (int k = 0; k < 2; ++k) dst[n][k] = *(const PG8_LAS bf16x8*)(lds + PG8_SB(b, h) + boff + n * 2048 + k * 1024); } while (0)
; #define PG8_MMA(ai, bj, At, Bt) do { __builtin_amdgcn_s_setprio(1); _Pragma("unroll") for (int m = 0; m < 4; ++m) _Pragma("unroll") for (int n = 0; n < 2; ++n) _Pragma("unroll") for (int k = 0; k < 2; ++k) \
;         acc[ai][bj][m][n] = __builtin_amdgcn_mfma_f32_16x16x32_bf16(Bt[n][k], At[m][k], acc[ai][bj][m][n], 0, 0, 0); __builtin_amdgcn_s_setprio(0); } while (0)
; #define PG8_WAIT_V(n) asm volatile("s_waitcnt vmcnt(" #n ")" ::: "memory")
; template <class Epi, class Sched, bool ALIGN_EPI = false, bool SP2 = false>
; __device__ __forceinline__ void gemm_phase(PG8_LAS unsigned char* lds, const Gemm g, const Sched& S, const Epi& E) {
;     ...
;             PG8_LDB(B0, 0, 0); PG8_LDB(B1, 0, 1); PG8_SCHED; PG8_LDA(At, 0, 0); PG8_STAGE(PG8_SA(1, 1), a1 + hstep, voffA);
;             PG8_WAIT_V(8); PG8_WAIT_L(0); PG8_BAR; PG8_MMA(0, 0, At, B0); PG8_MMA(0, 1, At, B1); PG8_BAR; PG8_SCHED;
;             PG8_LDA(At, 0, 1); PG8_STAGE(PG8_SB(0, 0), b2, voffB); PG8_STAGE(PG8_SB(0, 1), b2 + hstep, voffB); PG8_STAGE(PG8_SA(0, 0), a2, voffA);
;             PG8_WAIT_V(8); PG8_WAIT_L(0); PG8_BAR; PG8_MMA(1, 0, At, B0); PG8_MMA(1, 1, At, B1); PG8_BAR; PG8_SCHED;
;             PG8_LDB(B0, 1, 0); PG8_LDB(B1, 1, 1); PG8_SCHED; PG8_LDA(At, 1, 0); PG8_STAGE(PG8_SA(0, 1), a2 + hstep, voffA);
;             PG8_WAIT_V(8); PG8_WAIT_L(0); PG8_BAR; PG8_MMA(0, 0, At, B0); PG8_MMA(0, 1, At, B1); PG8_BAR; PG8_SCHED;
;             PG8_LDA(At, 1, 1); PG8_STAGE(PG8_SB(1, 0), b3, voffB); PG8_STAGE(PG8_SB(1, 1), b3 + hstep, voffB); PG8_STAGE(PG8_SA(1, 0), a3, voffA);
;             PG8_WAIT_V(8); PG8_WAIT_L(0); PG8_BAR; PG8_MMA(1, 0, At, B0); PG8_MMA(1, 1, At, B1); PG8_BAR; PG8_SCHED;
	s_setprio 1
	s_waitcnt lgkmcnt(0)
	v_mfma_f32_16x16x32_bf16 v[60:63], v[128:131], v[196:199], v[60:63]
	v_mfma_f32_16x16x32_bf16 v[56:59], v[158:161], v[196:199], v[56:59]
	v_mfma_f32_16x16x32_bf16 v[44:47], v[128:131], v[204:207], v[44:47]
	v_mfma_f32_16x16x32_bf16 v[40:43], v[158:161], v[204:207], v[40:43]
	v_mfma_f32_16x16x32_bf16 v[28:31], v[128:131], v[212:215], v[28:31]
	v_mfma_f32_16x16x32_bf16 v[24:27], v[158:161], v[212:215], v[24:27]
	v_mfma_f32_16x16x32_bf16 v[12:15], v[128:131], v[220:223], v[12:15]
	v_mfma_f32_16x16x32_bf16 v[8:11], v[158:161], v[220:223], v[8:11]
	v_mfma_f32_16x16x32_bf16 v[60:63], v[132:135], v[200:203], v[60:63]
	v_mfma_f32_16x16x32_bf16 v[56:59], v[176:179], v[200:203], v[56:59]
	v_mfma_f32_16x16x32_bf16 v[44:47], v[132:135], v[208:211], v[44:47]
	v_mfma_f32_16x16x32_bf16 v[40:43], v[176:179], v[208:211], v[40:43]
	v_mfma_f32_16x16x32_bf16 v[28:31], v[132:135], v[216:219], v[28:31]
	v_mfma_f32_16x16x32_bf16 v[24:27], v[176:179], v[216:219], v[24:27]
	v_mfma_f32_16x16x32_bf16 v[12:15], v[132:135], v[224:227], v[12:15]
	v_mfma_f32_16x16x32_bf16 v[8:11], v[176:179], v[224:227], v[8:11]
	s_setprio 0
	s_setprio 1
	v_mfma_f32_16x16x32_bf16 v[52:55], v[180:183], v[196:199], v[52:55]
	v_mfma_f32_16x16x32_bf16 v[48:51], v[188:191], v[196:199], v[48:51]
	v_mfma_f32_16x16x32_bf16 v[36:39], v[180:183], v[204:207], v[36:39]
	v_mfma_f32_16x16x32_bf16 v[32:35], v[188:191], v[204:207], v[32:35]
	v_mfma_f32_16x16x32_bf16 v[20:23], v[180:183], v[212:215], v[20:23]
	v_mfma_f32_16x16x32_bf16 v[16:19], v[188:191], v[212:215], v[16:19]
	v_mfma_f32_16x16x32_bf16 v[4:7], v[180:183], v[220:223], v[4:7]
	v_mfma_f32_16x16x32_bf16 v[0:3], v[188:191], v[220:223], v[0:3]
	v_mfma_f32_16x16x32_bf16 v[52:55], v[184:187], v[200:203], v[52:55]
	v_mfma_f32_16x16x32_bf16 v[48:51], v[192:195], v[200:203], v[48:51]
	v_mfma_f32_16x16x32_bf16 v[36:39], v[184:187], v[208:211], v[36:39]
	v_mfma_f32_16x16x32_bf16 v[32:35], v[192:195], v[208:211], v[32:35]
	v_mfma_f32_16x16x32_bf16 v[20:23], v[184:187], v[216:219], v[20:23]
	v_mfma_f32_16x16x32_bf16 v[16:19], v[192:195], v[216:219], v[16:19]
	v_mfma_f32_16x16x32_bf16 v[4:7], v[184:187], v[224:227], v[4:7]
	v_mfma_f32_16x16x32_bf16 v[0:3], v[192:195], v[224:227], v[0:3]
	s_setprio 0
	s_barrier
	s_add_i32 s76, 0, 0x18000
	v_add_u32_e32 v144, s76, v164
	s_add_i32 s77, 0, 0x1c000
	ds_read_b128 v[128:131], v144
	ds_read_b128 v[132:135], v144 offset:1024
	ds_read_b128 v[158:161], v144 offset:2048
	ds_read_b128 v[176:179], v144 offset:3072
	v_add_u32_e32 v144, s77, v164
	ds_read_b128 v[180:183], v144
	ds_read_b128 v[184:187], v144 offset:1024
	ds_read_b128 v[188:191], v144 offset:2048
	ds_read_b128 v[192:195], v144 offset:3072
	v_lshl_add_u64 v[230:231], s[52:53], 0, v[136:137]
	s_add_u32 s52, s52, 0x80000
	s_addc_u32 s53, s53, 0
	s_mov_b32 m0, s55
	v_lshl_add_u64 v[234:235], s[52:53], 0, v[136:137]
	ds_read_b128 v[196:199], v172 offset:32768
	ds_read_b128 v[200:203], v172 offset:33792
	ds_read_b128 v[204:207], v172 offset:34816
	ds_read_b128 v[208:211], v172 offset:35840
	ds_read_b128 v[212:215], v172 offset:36864
	ds_read_b128 v[216:219], v172 offset:37888
	ds_read_b128 v[220:223], v172 offset:38912
	ds_read_b128 v[224:227], v172 offset:39936
	global_load_lds_dwordx4 v[230:231], off
	s_mov_b32 m0, s56
	s_nop 0
	global_load_lds_dwordx4 v[232:233], off
	s_mov_b32 m0, s57
	s_nop 0
	global_load_lds_dwordx4 v[234:235], off
	v_lshl_add_u64 v[234:235], s[52:53], 0, v[140:141]
	s_mov_b32 m0, s58
	s_nop 0
	global_load_lds_dwordx4 v[234:235], off
	s_waitcnt vmcnt(8)
	s_waitcnt lgkmcnt(0)
	s_barrier
; #define PG8_STAGE(bufoff, gbase, voff) do { _Pragma("unroll") for (int _i = 0; _i < 2; ++_i) \
;         __builtin_amdgcn_global_load_lds((const unsigned*)((const char*)(gbase) + (voff)[_i]), (PG8_LAS unsigned*)(lds + (bufoff) + ldsw + _i * 8192), 16, 0, 0); } while (0)
; #define PG8_LDA(dst, b, h) do { _Pragma("unroll") for (int m = 0; m < 4; ++m) _Pragma("unroll") for (int k = 0; k < 2; ++k) dst[m][k] = *(const PG8_LAS bf16x8*)(lds + PG8_SA(b, h) + aoff + m * 2048 + k * 1024); } while (0)
; #define PG8_LDB(dst, b, h) do { _Pragma("unroll") for (int n = 0; n < 2; ++n) _Pragma("unroll") for (int k = 0; k < 2; ++k) dst[n][k] = *(const PG8_LAS bf16x8*)(lds + PG8_SB(b, h) + boff + n * 2048 + k * 1024); } while (0)
; template <class Epi, class Sched, bool ALIGN_EPI = false, bool SP2 = false>
; __device__ __forceinline__ void gemm_phase(PG8_LAS unsigned char* lds, const Gemm g, const Sched& S, const Epi& E) {
;     ...
;         for (int t = 0; t < nt; t += 2) {
;             const bool last = (t == nt - 2);
;             const char* a1 = cA + (size_t)(t + 1) * kstep;
;             const char* a2 = last ? nA : cA + (size_t)(t + 2) * kstep; const char* b2 = last ? nB : cB + (size_t)(t + 2) * kstep;
;             const char* a3 = a2 + kstep; const char* b3 = b2 + kstep;
;             if (last && has_next) S.a_ready(nxt);
;             if constexpr (SP2) {
;             PG8_LDB(B0, 0, 0); PG8_LDB(B1, 0, 1); PG8_SCHED; PG8_LDA(At, 0, 0); PG8_STAGE(PG8_SA(1, 1), a1 + hstep, voffA);
;             PG8_WAIT_V(8); PG8_WAIT_L(0); PG8_BAR; PG8_MMA(0, 0, At, B0); PG8_MMA(0, 1, At, B1); PG8_BAR; PG8_SCHED;
;             PG8_LDA(At, 0, 1); PG8_STAGE(PG8_SB(0, 0), b2, voffB); PG8_STAGE(PG8_SB(0, 1), b2 + hstep, voffB); PG8_STAGE(PG8_SA(0, 0), a2, voffA);
;             PG8_WAIT_V(8); PG8_WAIT_L(0); PG8_BAR; PG8_MMA(1, 0, At, B0); PG8_MMA(1, 1, At, B1); PG8_BAR; PG8_SCHED;
;             PG8_LDB(B0, 1, 0); PG8_LDB(B1, 1, 1); PG8_SCHED; PG8_LDA(At, 1, 0); PG8_STAGE(PG8_SA(0, 1), a2 + hstep, voffA);
;             PG8_WAIT_V(8); PG8_WAIT_L(0); PG8_BAR; PG8_MMA(0, 0, At, B0); PG8_MMA(0, 1, At, B1); PG8_BAR; PG8_SCHED;
;             PG8_LDA(At, 1, 1); PG8_STAGE(PG8_SB(1, 0), b3, voffB); PG8_STAGE(PG8_SB(1, 1), b3 + hstep, voffB); PG8_STAGE(PG8_SA(1, 0), a3, voffA);
;             PG8_WAIT_V(8); PG8_WAIT_L(0); PG8_BAR; PG8_MMA(1, 0, At, B0); PG8_MMA(1, 1, At, B1); PG8_BAR; PG8_SCHED;
	s_setprio 1
	s_waitcnt lgkmcnt(0)
	v_mfma_f32_16x16x32_bf16 v[124:127], v[128:131], v[196:199], v[124:127]
	v_mfma_f32_16x16x32_bf16 v[120:123], v[158:161], v[196:199], v[120:123]
	v_mfma_f32_16x16x32_bf16 v[108:111], v[128:131], v[204:207], v[108:111]
	v_mfma_f32_16x16x32_bf16 v[104:107], v[158:161], v[204:207], v[104:107]
	v_mfma_f32_16x16x32_bf16 v[92:95], v[128:131], v[212:215], v[92:95]
	v_mfma_f32_16x16x32_bf16 v[88:91], v[158:161], v[212:215], v[88:91]
	v_mfma_f32_16x16x32_bf16 v[76:79], v[128:131], v[220:223], v[76:79]
	v_mfma_f32_16x16x32_bf16 v[72:75], v[158:161], v[220:223], v[72:75]
	v_mfma_f32_16x16x32_bf16 v[124:127], v[132:135], v[200:203], v[124:127]
	v_mfma_f32_16x16x32_bf16 v[120:123], v[176:179], v[200:203], v[120:123]
	v_mfma_f32_16x16x32_bf16 v[108:111], v[132:135], v[208:211], v[108:111]
	v_mfma_f32_16x16x32_bf16 v[104:107], v[176:179], v[208:211], v[104:107]
	v_mfma_f32_16x16x32_bf16 v[92:95], v[132:135], v[216:219], v[92:95]
	v_mfma_f32_16x16x32_bf16 v[88:91], v[176:179], v[216:219], v[88:91]
	v_mfma_f32_16x16x32_bf16 v[76:79], v[132:135], v[224:227], v[76:79]
	v_mfma_f32_16x16x32_bf16 v[72:75], v[176:179], v[224:227], v[72:75]
	s_setprio 0
	s_setprio 1
	v_mfma_f32_16x16x32_bf16 v[116:119], v[180:183], v[196:199], v[116:119]
	v_mfma_f32_16x16x32_bf16 v[112:115], v[188:191], v[196:199], v[112:115]
	v_mfma_f32_16x16x32_bf16 v[100:103], v[180:183], v[204:207], v[100:103]
	v_mfma_f32_16x16x32_bf16 v[96:99], v[188:191], v[204:207], v[96:99]
	v_mfma_f32_16x16x32_bf16 v[84:87], v[180:183], v[212:215], v[84:87]
	v_mfma_f32_16x16x32_bf16 v[80:83], v[188:191], v[212:215], v[80:83]
	v_mfma_f32_16x16x32_bf16 v[68:71], v[180:183], v[220:223], v[68:71]
	v_mfma_f32_16x16x32_bf16 v[64:67], v[188:191], v[220:223], v[64:67]
	v_mfma_f32_16x16x32_bf16 v[116:119], v[184:187], v[200:203], v[116:119]
	v_mfma_f32_16x16x32_bf16 v[112:115], v[192:195], v[200:203], v[112:115]
	v_mfma_f32_16x16x32_bf16 v[100:103], v[184:187], v[208:211], v[100:103]
	v_mfma_f32_16x16x32_bf16 v[96:99], v[192:195], v[208:211], v[96:99]
	v_mfma_f32_16x16x32_bf16 v[84:87], v[184:187], v[216:219], v[84:87]
	v_mfma_f32_16x16x32_bf16 v[80:83], v[192:195], v[216:219], v[80:83]
	v_mfma_f32_16x16x32_bf16 v[68:71], v[184:187], v[224:227], v[68:71]
	v_mfma_f32_16x16x32_bf16 v[64:67], v[192:195], v[224:227], v[64:67]
	s_setprio 0
	s_barrier
	s_add_i32 s52, s76, s54
	v_lshl_add_u64 v[162:163], v[162:163], 0, s[12:13]
	s_mov_b32 m0, s52
	ds_read_b128 v[196:199], v172 offset:49152
	ds_read_b128 v[200:203], v172 offset:50176
	ds_read_b128 v[204:207], v172 offset:51200
	ds_read_b128 v[208:211], v172 offset:52224
	ds_read_b128 v[212:215], v172 offset:53248
	ds_read_b128 v[216:219], v172 offset:54272
	ds_read_b128 v[220:223], v172 offset:55296
	ds_read_b128 v[224:227], v172 offset:56320
	global_load_lds_dwordx4 v[162:163], off
	s_add_i32 m0, s52, 0x2000
	s_add_u32 s48, s48, 0x80080
	v_lshl_add_u64 v[162:163], v[228:229], 0, s[12:13]
	s_addc_u32 s49, s49, 0
	s_add_i32 s52, s77, s54
	global_load_lds_dwordx4 v[162:163], off
	v_lshl_add_u64 v[162:163], s[48:49], 0, v[138:139]
	s_mov_b32 m0, s52
	s_nop 0
	global_load_lds_dwordx4 v[162:163], off
	v_lshl_add_u64 v[162:163], s[48:49], 0, v[142:143]
	s_add_i32 m0, s52, 0x2000
	s_nop 0
	global_load_lds_dwordx4 v[162:163], off
	s_waitcnt vmcnt(6)
	s_waitcnt lgkmcnt(0)
	s_barrier
	s_setprio 1
	s_waitcnt lgkmcnt(0)
	v_mfma_f32_16x16x32_bf16 v[60:63], v[128:131], v[196:199], v[60:63]
	v_mfma_f32_16x16x32_bf16 v[56:59], v[158:161], v[196:199], v[56:59]
	v_mfma_f32_16x16x32_bf16 v[44:47], v[128:131], v[204:207], v[44:47]
	v_mfma_f32_16x16x32_bf16 v[40:43], v[158:161], v[204:207], v[40:43]
	v_mfma_f32_16x16x32_bf16 v[28:31], v[128:131], v[212:215], v[28:31]
	v_mfma_f32_16x16x32_bf16 v[24:27], v[158:161], v[212:215], v[24:27]
	v_mfma_f32_16x16x32_bf16 v[12:15], v[128:131], v[220:223], v[12:15]
	v_mfma_f32_16x16x32_bf16 v[8:11], v[158:161], v[220:223], v[8:11]
	v_mfma_f32_16x16x32_bf16 v[60:63], v[132:135], v[200:203], v[60:63]
	v_mfma_f32_16x16x32_bf16 v[56:59], v[176:179], v[200:203], v[56:59]
	v_mfma_f32_16x16x32_bf16 v[44:47], v[132:135], v[208:211], v[44:47]
	v_mfma_f32_16x16x32_bf16 v[40:43], v[176:179], v[208:211], v[40:43]
	v_mfma_f32_16x16x32_bf16 v[28:31], v[132:135], v[216:219], v[28:31]
	v_mfma_f32_16x16x32_bf16 v[24:27], v[176:179], v[216:219], v[24:27]
	v_mfma_f32_16x16x32_bf16 v[12:15], v[132:135], v[224:227], v[12:15]
	v_mfma_f32_16x16x32_bf16 v[8:11], v[176:179], v[224:227], v[8:11]
	s_setprio 0
	s_setprio 1
	v_mfma_f32_16x16x32_bf16 v[52:55], v[180:183], v[196:199], v[52:55]
	v_mfma_f32_16x16x32_bf16 v[48:51], v[188:191], v[196:199], v[48:51]
	v_mfma_f32_16x16x32_bf16 v[36:39], v[180:183], v[204:207], v[36:39]
	v_mfma_f32_16x16x32_bf16 v[32:35], v[188:191], v[204:207], v[32:35]
	v_mfma_f32_16x16x32_bf16 v[20:23], v[180:183], v[212:215], v[20:23]
	v_mfma_f32_16x16x32_bf16 v[16:19], v[188:191], v[212:215], v[16:19]
	v_mfma_f32_16x16x32_bf16 v[4:7], v[180:183], v[220:223], v[4:7]
	v_mfma_f32_16x16x32_bf16 v[0:3], v[188:191], v[220:223], v[0:3]
	v_mfma_f32_16x16x32_bf16 v[52:55], v[184:187], v[200:203], v[52:55]
	v_mfma_f32_16x16x32_bf16 v[48:51], v[192:195], v[200:203], v[48:51]
	v_mfma_f32_16x16x32_bf16 v[36:39], v[184:187], v[208:211], v[36:39]
	v_mfma_f32_16x16x32_bf16 v[32:35], v[192:195], v[208:211], v[32:35]
	v_mfma_f32_16x16x32_bf16 v[20:23], v[184:187], v[216:219], v[20:23]
	v_mfma_f32_16x16x32_bf16 v[16:19], v[192:195], v[216:219], v[16:19]
	v_mfma_f32_16x16x32_bf16 v[4:7], v[184:187], v[224:227], v[4:7]
	v_mfma_f32_16x16x32_bf16 v[0:3], v[192:195], v[224:227], v[0:3]
	s_setprio 0
	s_barrier
	s_add_i32 s75, s75, 2
	s_add_u32 s36, s36, 0x100
	s_addc_u32 s37, s37, 0
	s_add_u32 s35, s35, 0x100
	s_addc_u32 s74, s74, 0
	s_cmp_gt_u32 s75, 29
	s_cbranch_scc0 .LBB0_297
	s_and_b64 vcc, exec, s[14:15]
	s_cbranch_vccz .LBB0_300
	s_barrier

; __device__ __forceinline__ void partialSM(f32x16& p0, f32x16& p1, float& m_reg, float& mn, float& alpha) {
;     float pmax = p0[0];
; #pragma unroll
;     for (int r = 1; r < 16; ++r) pmax = fmaxf(pmax, p0[r]);
; #pragma unroll
;     for (int r = 0; r < 16; ++r) pmax = fmaxf(pmax, p1[r]);
;     { auto rr = __builtin_amdgcn_permlane32_swap(__float_as_uint(pmax), __float_as_uint(pmax), false, false);
;       pmax = fmaxf(__uint_as_float(rr[0]), __uint_as_float(rr[1])); }
;     constexpr float C2 = 1.4426950408889634f * SCALE;
;     if (__builtin_expect(__all((pmax - m_reg) * SCALE <= THR), 1)) { mn = m_reg; alpha = 1.f; }
;     else { mn = fmaxf(m_reg, pmax); alpha = __builtin_amdgcn_exp2f((m_reg - mn) * C2); m_reg = mn; }
;     const float mnL = -mn * C2;
; #pragma unroll
;     for (int r = 0; r < 16; ++r) p0[r] = fmaf(p0[r], C2, mnL);
; #pragma unroll
;     for (int r = 0; r < 16; ++r) p1[r] = fmaf(p1[r], C2, mnL);
; #pragma unroll
;     for (int r = 0; r < 16; ++r) p0[r] = __builtin_amdgcn_exp2f(p0[r]);
; }
; __device__ __forceinline__ void finishSM(f32x16& p0, f32x16& p1, float alpha, float& l_reg, bf16x8& pa0, bf16x8& pa1, bf16x8& pa2, bf16x8& pa3) {
; #pragma unroll
;     for (int r = 0; r < 16; ++r) p1[r] = __builtin_amdgcn_exp2f(p1[r]);
;     float ps = 0;
; #pragma unroll
;     for (int r = 0; r < 16; ++r) ps += p0[r];
; #pragma unroll
;     for (int r = 0; r < 16; ++r) ps += p1[r];
;     { auto rr = __builtin_amdgcn_permlane32_swap(__float_as_uint(ps), __float_as_uint(ps), false, false);
;       ps = __uint_as_float(rr[0]) + __uint_as_float(rr[1]); }
;     l_reg = l_reg * alpha + ps;
;     PK4(p0, 0, pa0); PK4(p0, 8, pa1); PK4(p1, 0, pa2); PK4(p1, 8, pa3);
; }
; __device__ __forceinline__ void attn_block(const BlockRef& cur, const BlockRef& nxt, char* lds, Seam& S) {
;     ...
;     float m_reg = -1e30f, l_reg = 0; f32x16 o[4] = {};
;     const int sr = tid >> 4, sc = (tid & 15) * 8, rr = tid >> 3, rc = (tid & 7) * 8;
;     const unsigned voff = (unsigned)(sr * 2048 + sc), roff = (unsigned)(rr * 64 + rc), qoff = (unsigned)((wid * QBLK + r32) * 2048 + hi * 8);
;     const int vst0 = v_st(sr, sc), vst1 = v_st(32 + sr, sc), kws = KSWZ(sr, sc * 2), kws2 = KSWZ(rr, (128 + rc) * 2);
;     const int vb0 = (int)(uintptr_t)V_lds + v_rd_base(lane);
;     ...
;     f32x16 pA0, pA1, pB0, pB1; float mnA, mnB, alA, alB; bf16x8 pa0, pa1, pa2, pa3;
;     SWRITE_HV(0); SBAR();
.LBB0_969:
	v_max_f32_e32 v33, 0xf149f2ca, v32
	v_cndmask_b32_e64 v148, v33, v199, s[0:1]
	v_mul_f32_e32 v32, 0xbdd53b94, v148
	v_fmamk_f32 v16, v16, 0x3dd53b94, v32
	v_exp_f32_e32 v159, v16
	v_sub_f32_e32 v16, 0xf149f2ca, v33
	v_mul_f32_e32 v16, 0x3dd53b94, v16
	v_exp_f32_e32 v16, v16
	v_fmamk_f32 v17, v17, 0x3dd53b94, v32
	v_fmamk_f32 v18, v18, 0x3dd53b94, v32
	v_fmamk_f32 v19, v19, 0x3dd53b94, v32
	v_fmamk_f32 v20, v20, 0x3dd53b94, v32
	v_fmamk_f32 v21, v21, 0x3dd53b94, v32
	v_fmamk_f32 v22, v22, 0x3dd53b94, v32
	v_fmamk_f32 v23, v23, 0x3dd53b94, v32
	v_fmamk_f32 v24, v24, 0x3dd53b94, v32
	v_fmamk_f32 v25, v25, 0x3dd53b94, v32
	v_fmamk_f32 v26, v26, 0x3dd53b94, v32
	v_fmamk_f32 v27, v27, 0x3dd53b94, v32
	v_fmamk_f32 v28, v28, 0x3dd53b94, v32
	v_fmamk_f32 v29, v29, 0x3dd53b94, v32
	v_fmamk_f32 v30, v30, 0x3dd53b94, v32
	v_fmamk_f32 v31, v31, 0x3dd53b94, v32
	v_cndmask_b32_e64 v209, v16, 1.0, s[0:1]
	s_and_b32 s0, s94, 0x3fffffc0
	v_exp_f32_e32 v161, v17
	v_exp_f32_e32 v157, v18
	v_exp_f32_e32 v160, v19
	v_exp_f32_e32 v156, v20
	v_exp_f32_e32 v158, v21
	v_exp_f32_e32 v154, v22
	v_exp_f32_e32 v155, v23
	v_exp_f32_e32 v150, v24
	v_exp_f32_e32 v153, v25
	s_waitcnt vmcnt(4)
	v_exp_f32_e32 v146, v26
	v_exp_f32_e32 v151, v27
	v_exp_f32_e32 v144, v28
	v_exp_f32_e32 v152, v29
	v_exp_f32_e32 v145, v30
	v_exp_f32_e32 v147, v31
	s_lshl_b32 s0, s0, 2
	s_add_i32 s0, s0, 0
	s_add_i32 s1, s68, 0x100
	s_add_i32 s0, s0, 0x14000
	s_waitcnt vmcnt(2)
	v_pk_fma_f32 v[128:129], v[14:15], s[90:91], v[32:33] op_sel_hi:[1,0,0]
	v_pk_fma_f32 v[130:131], v[12:13], s[90:91], v[32:33] op_sel_hi:[1,0,0]
	v_pk_fma_f32 v[132:133], v[10:11], s[90:91], v[32:33] op_sel_hi:[1,0,0]
	v_pk_fma_f32 v[134:135], v[8:9], s[90:91], v[32:33] op_sel_hi:[1,0,0]
	s_waitcnt vmcnt(1)
	v_pk_fma_f32 v[136:137], v[6:7], s[90:91], v[32:33] op_sel_hi:[1,0,0]
	v_pk_fma_f32 v[138:139], v[4:5], s[90:91], v[32:33] op_sel_hi:[1,0,0]
	s_waitcnt vmcnt(0)
	v_pk_fma_f32 v[140:141], v[2:3], s[90:91], v[32:33] op_sel_hi:[1,0,0]
	v_pk_fma_f32 v[142:143], v[0:1], s[90:91], v[32:33] op_sel_hi:[1,0,0]
	v_mov_b32_e32 v15, 0
	s_cmpk_lt_i32 s68, 0xffc0
	v_lshl_add_u32 v201, v167, 2, s0
	v_lshl_add_u32 v175, v183, 2, s0
	s_waitcnt lgkmcnt(0)
	s_barrier
	s_cbranch_scc1 .LBB0_989
	v_readfirstlane_b32 s8, v168
	s_nop 3
	s_cmp_ge_u32 s8, 0x100
	s_cbranch_scc0 .Lattn_prio_done
	s_setprio 1
.Lattn_prio_done:
	v_mov_b32_e32 v202, 0
	s_ashr_i32 s75, s1, 6
	s_mov_b32 s74, 2
	v_add_u32_e32 v210, s95, v191
	v_lshl_add_u64 v[176:177], s[36:37], 0, v[172:173]
	s_movk_i32 s68, 0xbf
	v_mov_b32_e32 v48, 0
	v_mov_b32_e32 v49, v202
	v_mov_b32_e32 v50, v202
	v_mov_b32_e32 v51, v202
	v_mov_b32_e32 v52, v202
	v_mov_b32_e32 v53, v202
	v_mov_b32_e32 v54, v202
	v_mov_b32_e32 v55, v202
	v_mov_b32_e32 v56, v202
	v_mov_b32_e32 v57, v202
	v_mov_b32_e32 v58, v202
	v_mov_b32_e32 v59, v202
	v_mov_b32_e32 v60, v202
	v_mov_b32_e32 v61, v202
	v_mov_b32_e32 v62, v202
	v_mov_b32_e32 v63, v202
	v_mov_b32_e32 v32, 0
	v_mov_b32_e32 v33, v202
	v_mov_b32_e32 v34, v202
	v_mov_b32_e32 v35, v202
	v_mov_b32_e32 v36, v202
	v_mov_b32_e32 v37, v202
	v_mov_b32_e32 v38, v202
	v_mov_b32_e32 v39, v202
	v_mov_b32_e32 v40, v202
	v_mov_b32_e32 v41, v202
	v_mov_b32_e32 v42, v202
	v_mov_b32_e32 v43, v202
	v_mov_b32_e32 v44, v202
	v_mov_b32_e32 v45, v202
	v_mov_b32_e32 v46, v202
	v_mov_b32_e32 v47, v202
	v_mov_b32_e32 v16, 0
	v_mov_b32_e32 v17, v202
	v_mov_b32_e32 v18, v202
	v_mov_b32_e32 v19, v202
	v_mov_b32_e32 v20, v202
	v_mov_b32_e32 v21, v202
	v_mov_b32_e32 v22, v202
	v_mov_b32_e32 v23, v202
	v_mov_b32_e32 v24, v202
	v_mov_b32_e32 v25, v202
	v_mov_b32_e32 v26, v202
	v_mov_b32_e32 v27, v202
	v_mov_b32_e32 v28, v202
	v_mov_b32_e32 v29, v202
	v_mov_b32_e32 v30, v202
	v_mov_b32_e32 v31, v202
	v_mov_b32_e32 v0, 0
	v_mov_b32_e32 v1, v202
	v_mov_b32_e32 v2, v202
	v_mov_b32_e32 v3, v202
	v_mov_b32_e32 v4, v202
	v_mov_b32_e32 v5, v202
	v_mov_b32_e32 v6, v202
	v_mov_b32_e32 v7, v202
	v_mov_b32_e32 v8, v202
	v_mov_b32_e32 v9, v202
	v_mov_b32_e32 v10, v202
	v_mov_b32_e32 v11, v202
	v_mov_b32_e32 v12, v202
	v_mov_b32_e32 v13, v202
	v_mov_b32_e32 v14, v202
	v_mov_b32_e32 v15, v202
	v_writelane_b32 v254, s1, 59
.LBB0_971:
	ds_read_b128 v[64:67], v194 offset:24576
	ds_read_b128 v[68:71], v194 offset:36864
	ds_read_b128 v[178:181], v195 offset:24576
	ds_read_b128 v[212:215], v195 offset:36864
	v_add_f32_e32 v149, 0, v159
	v_add_f32_e32 v149, v161, v149
	s_waitcnt lgkmcnt(3)
	v_mfma_f32_32x32x16_bf16 v[80:95], v[64:67], v[124:127], 0
	v_add_f32_e32 v149, v157, v149
	v_add_f32_e32 v149, v160, v149
	v_add_f32_e32 v149, v156, v149
	v_add_f32_e32 v149, v158, v149
	v_add_f32_e32 v149, v154, v149
	v_add_f32_e32 v149, v155, v149
	v_add_f32_e32 v149, v150, v149
	s_waitcnt lgkmcnt(2)
	v_mfma_f32_32x32x16_bf16 v[64:79], v[68:71], v[124:127], 0
	v_add_f32_e32 v149, v153, v149
	v_add_f32_e32 v149, v146, v149
	v_add_f32_e32 v149, v151, v149
	v_exp_f32_e32 v142, v142
	v_add_f32_e32 v149, v144, v149
	v_exp_f32_e32 v143, v143
	v_add_f32_e32 v149, v152, v149
	s_waitcnt lgkmcnt(1)
	v_mfma_f32_32x32x16_bf16 v[80:95], v[178:181], v[120:123], v[80:95]
	v_exp_f32_e32 v140, v140
	v_add_f32_e32 v149, v145, v149
	v_exp_f32_e32 v141, v141
	v_add_f32_e32 v149, v147, v149
	v_exp_f32_e32 v138, v138
	v_add_f32_e32 v149, v142, v149
	v_exp_f32_e32 v139, v139
	s_waitcnt lgkmcnt(0)
	v_mfma_f32_32x32x16_bf16 v[64:79], v[212:215], v[120:123], v[64:79]
	ds_read_b128 v[178:181], v196 offset:24576
	ds_read_b128 v[212:215], v196 offset:36864
	v_add_f32_e32 v149, v143, v149
	v_exp_f32_e32 v136, v136
	v_add_f32_e32 v149, v140, v149
	v_exp_f32_e32 v137, v137
	v_add_f32_e32 v149, v141, v149
	v_exp_f32_e32 v134, v134
	s_waitcnt lgkmcnt(1)
; __device__ __forceinline__ void finishSM(f32x16& p0, f32x16& p1, float alpha, float& l_reg, bf16x8& pa0, bf16x8& pa1, bf16x8& pa2, bf16x8& pa3) {
; #pragma unroll
;     for (int r = 0; r < 16; ++r) p1[r] = __builtin_amdgcn_exp2f(p1[r]);
;     float ps = 0;
; #pragma unroll
;     for (int r = 0; r < 16; ++r) ps += p0[r];
; #pragma unroll
;     for (int r = 0; r < 16; ++r) ps += p1[r];
;     { auto rr = __builtin_amdgcn_permlane32_swap(__float_as_uint(ps), __float_as_uint(ps), false, false);
;       ps = __uint_as_float(rr[0]) + __uint_as_float(rr[1]); }
;     l_reg = l_reg * alpha + ps;
;     PK4(p0, 0, pa0); PK4(p0, 8, pa1); PK4(p1, 0, pa2); PK4(p1, 8, pa3);
; }
; template <int KB>
; __device__ __forceinline__ void qkt(f32x16& p0, f32x16& p1, const char* K_lds, int r32, int hi, const bf16x8* qr, const char* qx) {
;     p0 = f32x16{}; p1 = f32x16{};
;     const char* kb[4];
; #pragma unroll
;     for (int dd = 0; dd < 4; ++dd) kb[dd] = K_lds + KB * SHM_K + KSWZ(r32, (dd * 16 + hi * 8) * 2);
; #pragma unroll
;     for (int d0 = 0; d0 < 12; ++d0) { const char* a = kb[d0 & 3] + (d0 >> 2) * 128;
;         bf16x8 b0 = *reinterpret_cast<const bf16x8*>(a);
;         bf16x8 b1 = *reinterpret_cast<const bf16x8*>(a + 32 * 384);
;         const bf16x8 q = d0 < 8 ? qr[d0 & 7] : *reinterpret_cast<const bf16x8*>(qx + (d0 - 8) * 1024);
;         p0 = __builtin_amdgcn_mfma_f32_32x32x16_bf16(b0, q, p0, 0, 0, 0);
;         p1 = __builtin_amdgcn_mfma_f32_32x32x16_bf16(b1, q, p1, 0, 0, 0); }
; }
; template <int VB>
; __device__ __forceinline__ void pv_tile(f32x16* o, int vb0, bf16x8 pa0, bf16x8 pa1, bf16x8 pa2, bf16x8 pa3) {
	v_mfma_f32_32x32x16_bf16 v[80:95], v[178:181], v[116:119], v[80:95]
	v_add_f32_e32 v149, v138, v149
	v_exp_f32_e32 v135, v135
	v_add_f32_e32 v149, v139, v149
	v_exp_f32_e32 v132, v132
	v_add_f32_e32 v149, v136, v149
	v_exp_f32_e32 v133, v133
	v_add_f32_e32 v149, v137, v149
	s_waitcnt lgkmcnt(0)
	v_mfma_f32_32x32x16_bf16 v[64:79], v[212:215], v[116:119], v[64:79]
	ds_read_b128 v[178:181], v197 offset:24576
	ds_read_b128 v[212:215], v197 offset:36864
	v_exp_f32_e32 v130, v130
	v_add_f32_e32 v149, v134, v149
	v_exp_f32_e32 v131, v131
	v_add_f32_e32 v149, v135, v149
	v_exp_f32_e32 v128, v128
	v_add_f32_e32 v149, v132, v149
	s_waitcnt lgkmcnt(1)
	v_mfma_f32_32x32x16_bf16 v[80:95], v[178:181], v[112:115], v[80:95]
	v_exp_f32_e32 v129, v129
	v_add_f32_e32 v149, v133, v149
	v_add_f32_e32 v149, v130, v149
	v_add_f32_e32 v149, v131, v149
	v_add_f32_e32 v149, v128, v149
	v_add_f32_e32 v211, v129, v149
	s_waitcnt lgkmcnt(0)
	v_mfma_f32_32x32x16_bf16 v[64:79], v[212:215], v[112:115], v[64:79]
	ds_read_b128 v[178:181], v194 offset:24704
	ds_read_b128 v[212:215], v194 offset:36992
	s_waitcnt lgkmcnt(1)
	v_mfma_f32_32x32x16_bf16 v[80:95], v[178:181], v[108:111], v[80:95]
	s_waitcnt lgkmcnt(0)
	v_mfma_f32_32x32x16_bf16 v[64:79], v[212:215], v[108:111], v[64:79]
	ds_read_b128 v[178:181], v195 offset:24704
	ds_read_b128 v[212:215], v195 offset:36992
	s_waitcnt lgkmcnt(1)
	v_mfma_f32_32x32x16_bf16 v[80:95], v[178:181], v[104:107], v[80:95]
	s_waitcnt lgkmcnt(0)
	v_mfma_f32_32x32x16_bf16 v[64:79], v[212:215], v[104:107], v[64:79]
	ds_read_b128 v[178:181], v196 offset:24704
	ds_read_b128 v[212:215], v196 offset:36992
	s_waitcnt lgkmcnt(1)
	v_mfma_f32_32x32x16_bf16 v[80:95], v[178:181], v[100:103], v[80:95]
	s_waitcnt lgkmcnt(0)
	v_mfma_f32_32x32x16_bf16 v[64:79], v[212:215], v[100:103], v[64:79]
	ds_read_b128 v[178:181], v197 offset:24704
	ds_read_b128 v[212:215], v197 offset:36992
	s_waitcnt lgkmcnt(1)
	v_mfma_f32_32x32x16_bf16 v[80:95], v[178:181], v[96:99], v[80:95]
	s_waitcnt lgkmcnt(0)
	v_mfma_f32_32x32x16_bf16 v[64:79], v[212:215], v[96:99], v[64:79]
	ds_read_b128 v[178:181], v194 offset:24832
	ds_read_b128 v[212:215], v194 offset:37120
	ds_read_b128 v[216:219], v204
	s_waitcnt lgkmcnt(0)
	v_mfma_f32_32x32x16_bf16 v[80:95], v[178:181], v[216:219], v[80:95]
	v_mfma_f32_32x32x16_bf16 v[64:79], v[212:215], v[216:219], v[64:79]
	ds_read_b128 v[178:181], v195 offset:24832
	ds_read_b128 v[212:215], v195 offset:37120
	ds_read_b128 v[216:219], v204 offset:1024
	s_waitcnt lgkmcnt(0)
	v_mfma_f32_32x32x16_bf16 v[80:95], v[178:181], v[216:219], v[80:95]
	v_mfma_f32_32x32x16_bf16 v[64:79], v[212:215], v[216:219], v[64:79]
	ds_read_b128 v[178:181], v196 offset:24832
	ds_read_b128 v[212:215], v196 offset:37120
	ds_read_b128 v[216:219], v204 offset:2048
	s_waitcnt lgkmcnt(0)
	v_mfma_f32_32x32x16_bf16 v[80:95], v[178:181], v[216:219], v[80:95]
	v_mfma_f32_32x32x16_bf16 v[64:79], v[212:215], v[216:219], v[64:79]
	ds_read_b128 v[178:181], v197 offset:24832
	ds_read_b128 v[212:215], v197 offset:37120
	ds_read_b128 v[216:219], v204 offset:3072
	s_waitcnt lgkmcnt(0)
	v_mfma_f32_32x32x16_bf16 v[80:95], v[178:181], v[216:219], v[80:95]
	v_mfma_f32_32x32x16_bf16 v[64:79], v[212:215], v[216:219], v[64:79]
	v_mov_b32_e32 v212, v211
	s_nop 1
	v_permlane32_swap_b32_e32 v211, v212
	v_cvt_pk_bf16_f32 v214, v159, v161
	v_cvt_pk_bf16_f32 v215, v157, v160
	v_cvt_pk_bf16_f32 v216, v156, v158
	v_cvt_pk_bf16_f32 v217, v154, v155
	v_cvt_pk_bf16_f32 v150, v150, v153
	v_cvt_pk_bf16_f32 v151, v146, v151
	v_cvt_pk_bf16_f32 v152, v144, v152
	v_cvt_pk_bf16_f32 v153, v145, v147
	v_cvt_pk_bf16_f32 v154, v142, v143
	v_cvt_pk_bf16_f32 v155, v140, v141
	v_cvt_pk_bf16_f32 v156, v138, v139
	v_cvt_pk_bf16_f32 v157, v136, v137
	v_cvt_pk_bf16_f32 v158, v134, v135
	v_cvt_pk_bf16_f32 v159, v132, v133
	v_cvt_pk_bf16_f32 v160, v130, v131
	v_cvt_pk_bf16_f32 v161, v128, v129
	s_nop 0
	v_permlane32_swap_b32_e32 v214, v216
	v_permlane32_swap_b32_e32 v215, v217
	v_permlane32_swap_b32_e32 v150, v152
	v_permlane32_swap_b32_e32 v151, v153
	v_permlane32_swap_b32_e32 v154, v156
	v_permlane32_swap_b32_e32 v155, v157
	v_permlane32_swap_b32_e32 v158, v160
	v_permlane32_swap_b32_e32 v159, v161
	v_lshl_add_u64 v[180:181], s[70:71], 0, v[170:171]
	v_add_co_u32_e32 v128, vcc, s76, v180
	v_lshl_add_u64 v[178:179], s[96:97], 0, v[170:171]
	s_nop 0
	v_addc_co_u32_e32 v129, vcc, 0, v181, vcc
	v_add_co_u32_e32 v132, vcc, s77, v180
	s_nop 1
	v_addc_co_u32_e32 v133, vcc, 0, v181, vcc
	v_add_co_u32_e32 v136, vcc, s76, v178
	s_nop 1
	v_addc_co_u32_e32 v137, vcc, 0, v179, vcc
	v_add_co_u32_e32 v140, vcc, s77, v178
	s_nop 1
	v_addc_co_u32_e32 v141, vcc, 0, v179, vcc
	global_load_dwordx4 v[136:139], v[136:137], off
	global_load_dwordx4 v[140:143], v[140:141], off
	global_load_dwordx4 v[144:147], v[176:177], off
	global_load_dwordx4 v[128:131], v[128:129], off
	global_load_dwordx4 v[132:135], v[132:133], off
	ds_read_b64_tr_b16 v[218:219], v188 offset:0
	ds_read_b64_tr_b16 v[220:221], v188 offset:0x800
	ds_read_b64_tr_b16 v[222:223], v188 offset:0x200
	ds_read_b64_tr_b16 v[224:225], v188 offset:0xa00
	ds_read_b64_tr_b16 v[226:227], v188 offset:0x1000
	ds_read_b64_tr_b16 v[228:229], v188 offset:0x1800
	ds_read_b64_tr_b16 v[230:231], v188 offset:0x1200
	ds_read_b64_tr_b16 v[232:233], v188 offset:0x1a00
	ds_read_b64_tr_b16 v[234:235], v188 offset:0x2000
	ds_read_b64_tr_b16 v[236:237], v188 offset:0x2800
	ds_read_b64_tr_b16 v[238:239], v188 offset:0x2200
	ds_read_b64_tr_b16 v[240:241], v188 offset:0x2a00
	ds_read_b64_tr_b16 v[242:243], v188 offset:0x3000
	ds_read_b64_tr_b16 v[244:245], v188 offset:0x3800
	ds_read_b64_tr_b16 v[246:247], v188 offset:0x3200
	ds_read_b64_tr_b16 v[248:249], v188 offset:0x3a00
	s_waitcnt lgkmcnt(14)
; __device__ __forceinline__ void mask_tile(f32x16& p0, f32x16& p1, int dq) {
;     const float NEG = -__builtin_inff();
; #pragma unroll
;     for (int r = 0; r < 16; ++r) { const int c = (r & 3) + 8 * (r >> 2); if (dq - c < 0) p0[r] = NEG; if (dq - c - 32 < 0) p1[r] = NEG; }
; }
; template <int VB>
; __device__ __forceinline__ void pv_tile(f32x16* o, int vb0, bf16x8 pa0, bf16x8 pa1, bf16x8 pa2, bf16x8 pa3) {
;     ...
;     PV_D2(0, 1); PV_D2(2, 3);
	s_nop 0
	v_mfma_f32_32x32x16_bf16 v[48:63], v[214:217], v[218:221], v[48:63]
	ds_read_b64_tr_b16 v[218:219], v188 offset:0x400
	ds_read_b64_tr_b16 v[220:221], v188 offset:0xc00
	s_waitcnt lgkmcnt(14)
	v_mfma_f32_32x32x16_bf16 v[32:47], v[214:217], v[222:225], v[32:47]
	ds_read_b64_tr_b16 v[222:223], v188 offset:0x600
	ds_read_b64_tr_b16 v[224:225], v188 offset:0xe00
	s_waitcnt lgkmcnt(14)
	v_mfma_f32_32x32x16_bf16 v[48:63], v[150:153], v[226:229], v[48:63]
	ds_read_b64_tr_b16 v[226:227], v188 offset:0x1400
	ds_read_b64_tr_b16 v[228:229], v188 offset:0x1c00
	s_waitcnt lgkmcnt(14)
	v_mfma_f32_32x32x16_bf16 v[32:47], v[150:153], v[230:233], v[32:47]
	ds_read_b64_tr_b16 v[230:231], v188 offset:0x1600
	ds_read_b64_tr_b16 v[232:233], v188 offset:0x1e00
	s_waitcnt lgkmcnt(14)
	v_mfma_f32_32x32x16_bf16 v[48:63], v[154:157], v[234:237], v[48:63]
	ds_read_b64_tr_b16 v[234:235], v188 offset:0x2400
	ds_read_b64_tr_b16 v[236:237], v188 offset:0x2c00
	s_waitcnt lgkmcnt(14)
	v_mfma_f32_32x32x16_bf16 v[32:47], v[154:157], v[238:241], v[32:47]
	ds_read_b64_tr_b16 v[238:239], v188 offset:0x2600
	ds_read_b64_tr_b16 v[240:241], v188 offset:0x2e00
	s_waitcnt lgkmcnt(14)
	v_mfma_f32_32x32x16_bf16 v[48:63], v[158:161], v[242:245], v[48:63]
	ds_read_b64_tr_b16 v[242:243], v188 offset:0x3400
	ds_read_b64_tr_b16 v[244:245], v188 offset:0x3c00
	s_waitcnt lgkmcnt(14)
	v_mfma_f32_32x32x16_bf16 v[32:47], v[158:161], v[246:249], v[32:47]
	ds_read_b64_tr_b16 v[250:251], v188 offset:0x3600
	ds_read_b64_tr_b16 v[252:253], v188 offset:0x3e00
	s_waitcnt lgkmcnt(14)
	v_mfma_f32_32x32x16_bf16 v[16:31], v[214:217], v[218:221], v[16:31]
	s_sub_i32 s0, s68, 64
	s_cmp_le_i32 s0, s95
	s_waitcnt lgkmcnt(12)
	v_mfma_f32_32x32x16_bf16 v[0:15], v[214:217], v[222:225], v[0:15]
	s_waitcnt lgkmcnt(10)
	v_mfma_f32_32x32x16_bf16 v[16:31], v[150:153], v[226:229], v[16:31]
	s_waitcnt lgkmcnt(8)
	v_mfma_f32_32x32x16_bf16 v[0:15], v[150:153], v[230:233], v[0:15]
	s_waitcnt lgkmcnt(6)
	v_mfma_f32_32x32x16_bf16 v[16:31], v[154:157], v[234:237], v[16:31]
	s_waitcnt lgkmcnt(4)
	v_mfma_f32_32x32x16_bf16 v[0:15], v[154:157], v[238:241], v[0:15]
	s_waitcnt lgkmcnt(2)
	v_mfma_f32_32x32x16_bf16 v[16:31], v[158:161], v[242:245], v[16:31]
	s_waitcnt lgkmcnt(0)
	v_mfma_f32_32x32x16_bf16 v[0:15], v[158:161], v[250:253], v[0:15]
	s_waitcnt vmcnt(2)
	ds_write_b128 v169, v[136:139]
	ds_write_b128 v169, v[140:143] offset:12288
	ds_write_b128 v182, v[144:147]
	s_cbranch_scc1 .LBB0_973
	v_add_u32_e32 v149, 64, v210
	v_cmp_gt_i32_e64 s[64:65], 26, v149
	v_cmp_gt_i32_e64 s[66:67], 27, v149
	v_cmp_gt_i32_e64 s[62:63], 25, v149
	s_and_b64 s[64:65], s[66:67], s[64:65]
	v_cmp_gt_i32_e64 s[60:61], 24, v149
	s_and_b64 s[62:63], s[64:65], s[62:63]
	v_cmp_gt_i32_e64 s[58:59], 19, v149
	s_and_b64 s[60:61], s[62:63], s[60:61]
	v_cmp_gt_i32_e64 s[56:57], 18, v149
	s_and_b64 s[58:59], s[60:61], s[58:59]
	v_cmp_gt_i32_e64 s[54:55], 17, v149
	s_and_b64 s[56:57], s[58:59], s[56:57]
	v_cmp_gt_i32_e64 s[52:53], 16, v149
	s_and_b64 s[54:55], s[56:57], s[54:55]
	v_cmp_gt_i32_e64 s[50:51], 11, v149
	s_and_b64 s[52:53], s[54:55], s[52:53]
	v_cmp_gt_i32_e64 s[48:49], 10, v149
	s_and_b64 s[50:51], s[52:53], s[50:51]
	v_cmp_gt_i32_e64 s[46:47], 9, v149
	s_and_b64 s[48:49], s[50:51], s[48:49]
	v_cmp_gt_i32_e64 s[44:45], 8, v149
	s_and_b64 s[46:47], s[48:49], s[46:47]
	v_cmp_gt_i32_e64 s[42:43], 3, v149
	s_and_b64 s[44:45], s[46:47], s[44:45]
	v_cmp_gt_i32_e64 s[40:41], 2, v149
	s_and_b64 s[42:43], s[44:45], s[42:43]
	v_cmp_gt_i32_e64 s[38:39], 1, v149
	s_and_b64 s[40:41], s[42:43], s[40:41]
	v_cmp_gt_i32_e64 s[34:35], 0, v149
	s_and_b64 s[38:39], s[40:41], s[38:39]
	s_and_b64 s[34:35], s[38:39], s[34:35]
	v_cmp_gt_i32_e64 s[30:31], 58, v149
	v_cndmask_b32_e64 v80, v80, v198, s[34:35]
	v_cmp_gt_i32_e64 s[34:35], 59, v149
	v_cmp_gt_i32_e64 s[28:29], 57, v149
	s_and_b64 s[30:31], s[34:35], s[30:31]
	v_cmp_gt_i32_e64 s[26:27], 56, v149
	s_and_b64 s[28:29], s[30:31], s[28:29]
	v_cmp_gt_i32_e64 s[24:25], 51, v149
	s_and_b64 s[26:27], s[28:29], s[26:27]
	v_cmp_gt_i32_e64 s[22:23], 50, v149
	s_and_b64 s[24:25], s[26:27], s[24:25]
	v_cmp_gt_i32_e64 s[20:21], 49, v149
	s_and_b64 s[22:23], s[24:25], s[22:23]
	v_cmp_gt_i32_e64 s[18:19], 48, v149
	s_and_b64 s[20:21], s[22:23], s[20:21]
	v_cmp_gt_i32_e64 s[16:17], 43, v149
	s_and_b64 s[18:19], s[20:21], s[18:19]
	v_cmp_gt_i32_e64 s[14:15], 42, v149
	s_and_b64 s[16:17], s[18:19], s[16:17]
	v_cmp_gt_i32_e64 s[12:13], 41, v149
	s_and_b64 s[14:15], s[16:17], s[14:15]
	v_cmp_gt_i32_e64 s[10:11], 40, v149
	s_and_b64 s[12:13], s[14:15], s[12:13]
	v_cmp_gt_i32_e64 s[8:9], 35, v149
	s_and_b64 s[10:11], s[12:13], s[10:11]
	v_cmp_gt_i32_e64 s[6:7], 34, v149
	s_and_b64 s[8:9], s[10:11], s[8:9]
	v_cmp_gt_i32_e64 s[0:1], 33, v149
	s_and_b64 s[6:7], s[8:9], s[6:7]
	v_cmp_gt_i32_e32 vcc, 32, v149
	s_and_b64 s[0:1], s[6:7], s[0:1]
	s_and_b64 vcc, s[0:1], vcc
	v_cndmask_b32_e64 v95, v95, v198, s[66:67]
	v_cndmask_b32_e64 v94, v94, v198, s[64:65]
	v_cndmask_b32_e64 v93, v93, v198, s[62:63]
	v_cndmask_b32_e64 v92, v92, v198, s[60:61]
	v_cndmask_b32_e64 v91, v91, v198, s[58:59]
	v_cndmask_b32_e64 v90, v90, v198, s[56:57]
	v_cndmask_b32_e64 v89, v89, v198, s[54:55]
	v_cndmask_b32_e64 v88, v88, v198, s[52:53]
	v_cndmask_b32_e64 v87, v87, v198, s[50:51]
	v_cndmask_b32_e64 v86, v86, v198, s[48:49]
	v_cndmask_b32_e64 v85, v85, v198, s[46:47]
	v_cndmask_b32_e64 v84, v84, v198, s[44:45]
	v_cndmask_b32_e64 v83, v83, v198, s[42:43]
	v_cndmask_b32_e64 v82, v82, v198, s[40:41]
	v_cndmask_b32_e64 v81, v81, v198, s[38:39]
	v_cndmask_b32_e64 v79, v79, v198, s[34:35]
	v_cndmask_b32_e64 v78, v78, v198, s[30:31]
	v_cndmask_b32_e64 v77, v77, v198, s[28:29]
	v_cndmask_b32_e64 v76, v76, v198, s[26:27]
	v_cndmask_b32_e64 v75, v75, v198, s[24:25]
	v_cndmask_b32_e64 v74, v74, v198, s[22:23]
	v_cndmask_b32_e64 v73, v73, v198, s[20:21]
	v_cndmask_b32_e64 v72, v72, v198, s[18:19]
	v_cndmask_b32_e64 v71, v71, v198, s[16:17]
	v_cndmask_b32_e64 v70, v70, v198, s[14:15]
	v_cndmask_b32_e64 v69, v69, v198, s[12:13]
	v_cndmask_b32_e64 v68, v68, v198, s[10:11]
	v_cndmask_b32_e64 v67, v67, v198, s[8:9]
	v_cndmask_b32_e64 v66, v66, v198, s[6:7]
	v_cndmask_b32_e64 v65, v65, v198, s[0:1]
	v_cndmask_b32_e32 v64, v64, v198, vcc
; __device__ __forceinline__ void partialSM(f32x16& p0, f32x16& p1, float& m_reg, float& mn, float& alpha) {
;     float pmax = p0[0];
; #pragma unroll
;     for (int r = 1; r < 16; ++r) pmax = fmaxf(pmax, p0[r]);
; #pragma unroll
;     for (int r = 0; r < 16; ++r) pmax = fmaxf(pmax, p1[r]);
;     { auto rr = __builtin_amdgcn_permlane32_swap(__float_as_uint(pmax), __float_as_uint(pmax), false, false);
;       pmax = fmaxf(__uint_as_float(rr[0]), __uint_as_float(rr[1])); }
;     constexpr float C2 = 1.4426950408889634f * SCALE;
;     if (__builtin_expect(__all((pmax - m_reg) * SCALE <= THR), 1)) { mn = m_reg; alpha = 1.f; }
;     else { mn = fmaxf(m_reg, pmax); alpha = __builtin_amdgcn_exp2f((m_reg - mn) * C2); m_reg = mn; }
;     const float mnL = -mn * C2;
; #pragma unroll
;     for (int r = 0; r < 16; ++r) p0[r] = fmaf(p0[r], C2, mnL);
; #pragma unroll
;     for (int r = 0; r < 16; ++r) p1[r] = fmaf(p1[r], C2, mnL);
; #pragma unroll
;     for (int r = 0; r < 16; ++r) p0[r] = __builtin_amdgcn_exp2f(p0[r]);
; }
.LBB0_973:
	v_max_f32_e32 v149, v81, v81
	v_max_f32_e32 v150, v80, v80
	v_max_f32_e32 v149, v150, v149
	v_max3_f32 v149, v149, v82, v83
	v_max3_f32 v149, v149, v84, v85
	v_max3_f32 v149, v149, v86, v87
	v_max3_f32 v149, v149, v88, v89
	v_max3_f32 v149, v149, v90, v91
	v_max3_f32 v149, v149, v92, v93
	v_max3_f32 v149, v149, v94, v95
	v_max3_f32 v149, v149, v64, v65
	v_max3_f32 v149, v149, v66, v67
	v_max3_f32 v149, v149, v68, v69
	v_max3_f32 v149, v149, v70, v71
	v_max3_f32 v149, v149, v72, v73
	v_max3_f32 v149, v149, v74, v75
	v_max3_f32 v149, v149, v76, v77
	v_max3_f32 v149, v149, v78, v79
	v_mov_b32_e32 v150, v149
	s_nop 1
	v_permlane32_swap_b32_e32 v149, v150
	v_max_f32_e32 v150, v150, v150
	v_max_f32_e32 v149, v149, v149
	v_max_f32_e32 v149, v149, v150
	v_max_f32_e32 v151, v148, v148
	v_sub_f32_e32 v150, v149, v148
	v_max_f32_e32 v149, v151, v149
	v_sub_f32_e32 v151, v148, v149
	v_mul_f32_e32 v151, 0x3dd53b94, v151
	v_mul_f32_e32 v150, 0x3d93cd3a, v150
	v_exp_f32_e32 v151, v151
	v_cmp_ge_f32_e32 vcc, s33, v150
	s_cmp_eq_u64 vcc, exec
	s_cselect_b64 s[6:7], -1, 0
	s_barrier
	s_waitcnt vmcnt(0)
	v_cndmask_b32_e64 v213, v151, 1.0, s[6:7]
	v_cmp_gt_f32_e32 vcc, 1.0, v213
	ds_write_b128 v205, v[128:131] offset:49152
	ds_write_b128 v206, v[132:135] offset:49152
	s_cbranch_vccz .LBB0_977
	s_and_saveexec_b64 s[0:1], s[2:3]
	ds_write_b32 v201, v213 offset:128
	s_or_b64 exec, exec, s[0:1]
	s_waitcnt lgkmcnt(0)
	ds_read_b128 v[150:153], v175 offset:224
	ds_read_b128 v[154:157], v175 offset:192
	ds_read_b128 v[158:161], v175 offset:160
	ds_read_b128 v[214:217], v175 offset:128
	s_waitcnt lgkmcnt(3)
	v_pk_mul_f32 v[62:63], v[62:63], v[152:153]
	s_waitcnt lgkmcnt(2)
	v_pk_mul_f32 v[58:59], v[58:59], v[156:157]
	s_waitcnt lgkmcnt(1)
	v_pk_mul_f32 v[54:55], v[54:55], v[160:161]
	s_waitcnt lgkmcnt(0)
	v_pk_mul_f32 v[50:51], v[50:51], v[216:217]
	v_pk_mul_f32 v[60:61], v[60:61], v[150:151]
	v_pk_mul_f32 v[56:57], v[56:57], v[154:155]
	v_pk_mul_f32 v[52:53], v[52:53], v[158:159]
	v_pk_mul_f32 v[48:49], v[48:49], v[214:215]
	v_pk_mul_f32 v[46:47], v[46:47], v[152:153]
	v_pk_mul_f32 v[42:43], v[42:43], v[156:157]
	v_pk_mul_f32 v[38:39], v[38:39], v[160:161]
	v_pk_mul_f32 v[34:35], v[34:35], v[216:217]
	v_pk_mul_f32 v[44:45], v[44:45], v[150:151]
	v_pk_mul_f32 v[40:41], v[40:41], v[154:155]
	v_pk_mul_f32 v[36:37], v[36:37], v[158:159]
	v_pk_mul_f32 v[32:33], v[32:33], v[214:215]
	v_pk_mul_f32 v[30:31], v[30:31], v[152:153]
	v_pk_mul_f32 v[26:27], v[26:27], v[156:157]
	v_pk_mul_f32 v[22:23], v[22:23], v[160:161]
	v_pk_mul_f32 v[18:19], v[18:19], v[216:217]
	v_pk_mul_f32 v[28:29], v[28:29], v[150:151]
	v_pk_mul_f32 v[24:25], v[24:25], v[154:155]
	v_pk_mul_f32 v[20:21], v[20:21], v[158:159]
	v_pk_mul_f32 v[16:17], v[16:17], v[214:215]
	v_pk_mul_f32 v[14:15], v[14:15], v[152:153]
	v_pk_mul_f32 v[10:11], v[10:11], v[156:157]
	v_pk_mul_f32 v[6:7], v[6:7], v[160:161]
	v_pk_mul_f32 v[2:3], v[2:3], v[216:217]
	v_pk_mul_f32 v[12:13], v[12:13], v[150:151]
	v_pk_mul_f32 v[8:9], v[8:9], v[154:155]
	v_pk_mul_f32 v[4:5], v[4:5], v[158:159]
	v_pk_mul_f32 v[0:1], v[0:1], v[214:215]
.LBB0_977:
	v_cndmask_b32_e64 v214, v149, v148, s[6:7]
	v_mul_f32_e32 v215, 0xbdd53b94, v214
	v_fmamk_f32 v80, v80, 0x3dd53b94, v215
	v_fmamk_f32 v81, v81, 0x3dd53b94, v215
	v_fmamk_f32 v82, v82, 0x3dd53b94, v215
	v_fmamk_f32 v83, v83, 0x3dd53b94, v215
	v_fmamk_f32 v84, v84, 0x3dd53b94, v215
	v_fmamk_f32 v85, v85, 0x3dd53b94, v215
	v_fmamk_f32 v86, v86, 0x3dd53b94, v215
	v_fmamk_f32 v87, v87, 0x3dd53b94, v215
	v_fmamk_f32 v88, v88, 0x3dd53b94, v215
	v_fmamk_f32 v89, v89, 0x3dd53b94, v215
	v_fmamk_f32 v90, v90, 0x3dd53b94, v215
	v_fmamk_f32 v91, v91, 0x3dd53b94, v215
	v_fmamk_f32 v92, v92, 0x3dd53b94, v215
	v_fmamk_f32 v93, v93, 0x3dd53b94, v215
	v_fmamk_f32 v94, v94, 0x3dd53b94, v215
	v_fmamk_f32 v95, v95, 0x3dd53b94, v215
	v_exp_f32_e32 v148, v80
	v_exp_f32_e32 v163, v81
	v_exp_f32_e32 v149, v82
	v_exp_f32_e32 v162, v83
	v_exp_f32_e32 v150, v84
	v_exp_f32_e32 v161, v85
	v_exp_f32_e32 v151, v86
	v_exp_f32_e32 v160, v87
	v_exp_f32_e32 v152, v88
	v_exp_f32_e32 v159, v89
	v_exp_f32_e32 v153, v90
	v_exp_f32_e32 v158, v91
	v_exp_f32_e32 v154, v92
	v_exp_f32_e32 v157, v93
	v_exp_f32_e32 v155, v94
	v_exp_f32_e32 v156, v95
	v_fmamk_f32 v224, v64, 0x3dd53b94, v215
	v_fmamk_f32 v225, v65, 0x3dd53b94, v215
	v_fmamk_f32 v226, v66, 0x3dd53b94, v215
	v_fmamk_f32 v227, v67, 0x3dd53b94, v215
	v_fmamk_f32 v228, v68, 0x3dd53b94, v215
	v_fmamk_f32 v217, v69, 0x3dd53b94, v215
	v_fmamk_f32 v218, v70, 0x3dd53b94, v215
	v_fmamk_f32 v219, v71, 0x3dd53b94, v215
	v_fmamk_f32 v220, v72, 0x3dd53b94, v215
	v_fmamk_f32 v221, v73, 0x3dd53b94, v215
	v_fmamk_f32 v222, v74, 0x3dd53b94, v215
	v_fmamk_f32 v223, v75, 0x3dd53b94, v215
	v_fmamk_f32 v216, v76, 0x3dd53b94, v215
	v_fmamk_f32 v229, v77, 0x3dd53b94, v215
	v_fmamk_f32 v230, v78, 0x3dd53b94, v215
	v_fmac_f32_e32 v215, 0x3dd53b94, v79
	s_waitcnt lgkmcnt(0)
	s_barrier
; __device__ __forceinline__ void finishSM(f32x16& p0, f32x16& p1, float alpha, float& l_reg, bf16x8& pa0, bf16x8& pa1, bf16x8& pa2, bf16x8& pa3) {
; #pragma unroll
;     for (int r = 0; r < 16; ++r) p1[r] = __builtin_amdgcn_exp2f(p1[r]);
;     float ps = 0;
; #pragma unroll
;     for (int r = 0; r < 16; ++r) ps += p0[r];
; #pragma unroll
;     for (int r = 0; r < 16; ++r) ps += p1[r];
;     { auto rr = __builtin_amdgcn_permlane32_swap(__float_as_uint(ps), __float_as_uint(ps), false, false);
;       ps = __uint_as_float(rr[0]) + __uint_as_float(rr[1]); }
;     l_reg = l_reg * alpha + ps;
;     PK4(p0, 0, pa0); PK4(p0, 8, pa1); PK4(p1, 0, pa2); PK4(p1, 8, pa3);
; }
; template <int KB>
; __device__ __forceinline__ void qkt(f32x16& p0, f32x16& p1, const char* K_lds, int r32, int hi, const bf16x8* qr, const char* qx) {
;     p0 = f32x16{}; p1 = f32x16{};
;     const char* kb[4];
; #pragma unroll
;     for (int dd = 0; dd < 4; ++dd) kb[dd] = K_lds + KB * SHM_K + KSWZ(r32, (dd * 16 + hi * 8) * 2);
; #pragma unroll
;     for (int d0 = 0; d0 < 12; ++d0) { const char* a = kb[d0 & 3] + (d0 >> 2) * 128;
;         bf16x8 b0 = *reinterpret_cast<const bf16x8*>(a);
;         bf16x8 b1 = *reinterpret_cast<const bf16x8*>(a + 32 * 384);
;         const bf16x8 q = d0 < 8 ? qr[d0 & 7] : *reinterpret_cast<const bf16x8*>(qx + (d0 - 8) * 1024);
;         p0 = __builtin_amdgcn_mfma_f32_32x32x16_bf16(b0, q, p0, 0, 0, 0);
;         p1 = __builtin_amdgcn_mfma_f32_32x32x16_bf16(b1, q, p1, 0, 0, 0); }
; }
	ds_read_b128 v[64:67], v194
	ds_read_b128 v[68:71], v194 offset:12288
	ds_read_b128 v[232:235], v195
	ds_read_b128 v[236:239], v195 offset:12288
	v_exp_f32_e32 v224, v224
	v_exp_f32_e32 v225, v225
	s_waitcnt lgkmcnt(3)
	v_mfma_f32_32x32x16_bf16 v[80:95], v[64:67], v[124:127], 0
	v_exp_f32_e32 v226, v226
	v_exp_f32_e32 v227, v227
	v_exp_f32_e32 v228, v228
	v_exp_f32_e32 v217, v217
	v_exp_f32_e32 v218, v218
	v_exp_f32_e32 v219, v219
	v_exp_f32_e32 v220, v220
	s_waitcnt lgkmcnt(2)
	v_mfma_f32_32x32x16_bf16 v[64:79], v[68:71], v[124:127], 0
	v_exp_f32_e32 v221, v221
	v_exp_f32_e32 v222, v222
	v_exp_f32_e32 v223, v223
	v_exp_f32_e32 v231, v216
	v_exp_f32_e32 v229, v229
	v_exp_f32_e32 v230, v230
	s_waitcnt lgkmcnt(1)
	v_mfma_f32_32x32x16_bf16 v[80:95], v[232:235], v[120:123], v[80:95]
	s_waitcnt lgkmcnt(0)
	v_mfma_f32_32x32x16_bf16 v[64:79], v[236:239], v[120:123], v[64:79]
	ds_read_b128 v[232:235], v196
	ds_read_b128 v[236:239], v196 offset:12288
	s_waitcnt lgkmcnt(1)
	v_mfma_f32_32x32x16_bf16 v[80:95], v[232:235], v[116:119], v[80:95]
	s_waitcnt lgkmcnt(0)
	v_mfma_f32_32x32x16_bf16 v[64:79], v[236:239], v[116:119], v[64:79]
	ds_read_b128 v[232:235], v197
	ds_read_b128 v[236:239], v197 offset:12288
	s_waitcnt lgkmcnt(1)
	v_mfma_f32_32x32x16_bf16 v[80:95], v[232:235], v[112:115], v[80:95]
	s_waitcnt lgkmcnt(0)
	v_mfma_f32_32x32x16_bf16 v[64:79], v[236:239], v[112:115], v[64:79]
	ds_read_b128 v[232:235], v194 offset:128
	ds_read_b128 v[236:239], v194 offset:12416
	s_waitcnt lgkmcnt(1)
	v_mfma_f32_32x32x16_bf16 v[80:95], v[232:235], v[108:111], v[80:95]
	s_waitcnt lgkmcnt(0)
	v_mfma_f32_32x32x16_bf16 v[64:79], v[236:239], v[108:111], v[64:79]
	ds_read_b128 v[232:235], v195 offset:128
	ds_read_b128 v[236:239], v195 offset:12416
	s_waitcnt lgkmcnt(1)
	v_mfma_f32_32x32x16_bf16 v[80:95], v[232:235], v[104:107], v[80:95]
	s_waitcnt lgkmcnt(0)
	v_mfma_f32_32x32x16_bf16 v[64:79], v[236:239], v[104:107], v[64:79]
	ds_read_b128 v[232:235], v196 offset:128
	ds_read_b128 v[236:239], v196 offset:12416
	s_waitcnt lgkmcnt(1)
	v_mfma_f32_32x32x16_bf16 v[80:95], v[232:235], v[100:103], v[80:95]
	s_waitcnt lgkmcnt(0)
	v_mfma_f32_32x32x16_bf16 v[64:79], v[236:239], v[100:103], v[64:79]
	ds_read_b128 v[232:235], v197 offset:128
	ds_read_b128 v[236:239], v197 offset:12416
	s_waitcnt lgkmcnt(1)
	v_mfma_f32_32x32x16_bf16 v[80:95], v[232:235], v[96:99], v[80:95]
	s_waitcnt lgkmcnt(0)
	v_mfma_f32_32x32x16_bf16 v[64:79], v[236:239], v[96:99], v[64:79]
	ds_read_b128 v[232:235], v194 offset:256
	ds_read_b128 v[236:239], v194 offset:12544
	ds_read_b128 v[240:243], v204
	s_waitcnt lgkmcnt(0)
	v_mfma_f32_32x32x16_bf16 v[80:95], v[232:235], v[240:243], v[80:95]
	v_mfma_f32_32x32x16_bf16 v[64:79], v[236:239], v[240:243], v[64:79]
	ds_read_b128 v[232:235], v195 offset:256
	ds_read_b128 v[236:239], v195 offset:12544
	ds_read_b128 v[240:243], v204 offset:1024
	s_waitcnt lgkmcnt(0)
	v_mfma_f32_32x32x16_bf16 v[80:95], v[232:235], v[240:243], v[80:95]
	v_mfma_f32_32x32x16_bf16 v[64:79], v[236:239], v[240:243], v[64:79]
	ds_read_b128 v[232:235], v196 offset:256
	ds_read_b128 v[236:239], v196 offset:12544
	ds_read_b128 v[240:243], v204 offset:2048
	s_waitcnt lgkmcnt(0)
	v_mfma_f32_32x32x16_bf16 v[80:95], v[232:235], v[240:243], v[80:95]
	v_mfma_f32_32x32x16_bf16 v[64:79], v[236:239], v[240:243], v[64:79]
	ds_read_b128 v[232:235], v197 offset:256
	ds_read_b128 v[236:239], v197 offset:12544
	ds_read_b128 v[240:243], v204 offset:3072
	s_waitcnt lgkmcnt(0)
	v_mfma_f32_32x32x16_bf16 v[80:95], v[232:235], v[240:243], v[80:95]
	v_exp_f32_e32 v232, v215
	v_add_f32_e32 v215, 0, v148
	v_add_f32_e32 v215, v163, v215
	v_add_f32_e32 v215, v149, v215
	v_add_f32_e32 v215, v162, v215
	v_add_f32_e32 v215, v150, v215
	v_add_f32_e32 v215, v161, v215
	v_add_f32_e32 v215, v151, v215
	v_add_f32_e32 v215, v160, v215
	v_add_f32_e32 v215, v152, v215
	v_add_f32_e32 v215, v159, v215
	v_add_f32_e32 v215, v153, v215
	v_add_f32_e32 v215, v158, v215
	v_add_f32_e32 v215, v154, v215
	v_add_f32_e32 v215, v157, v215
	v_add_f32_e32 v215, v155, v215
	v_add_f32_e32 v215, v156, v215
	v_add_f32_e32 v215, v224, v215
	v_add_f32_e32 v215, v225, v215
	v_add_f32_e32 v215, v226, v215
	v_add_f32_e32 v215, v227, v215
	v_add_f32_e32 v215, v228, v215
	v_add_f32_e32 v215, v217, v215
	v_add_f32_e32 v215, v218, v215
	v_add_f32_e32 v215, v219, v215
	v_add_f32_e32 v215, v220, v215
	v_add_f32_e32 v215, v221, v215
	v_mfma_f32_32x32x16_bf16 v[64:79], v[236:239], v[240:243], v[64:79]
	v_add_f32_e32 v215, v222, v215
	v_add_f32_e32 v215, v223, v215
	v_add_f32_e32 v215, v231, v215
	v_add_f32_e32 v215, v229, v215
	v_add_f32_e32 v215, v230, v215
	v_add_f32_e32 v215, v232, v215
	v_mov_b32_e32 v216, v215
	v_cvt_pk_bf16_f32 v148, v148, v163
	v_cvt_pk_bf16_f32 v149, v149, v162
	v_cvt_pk_bf16_f32 v150, v150, v161
	v_cvt_pk_bf16_f32 v151, v151, v160
	v_cvt_pk_bf16_f32 v152, v152, v159
	v_cvt_pk_bf16_f32 v153, v153, v158
	v_cvt_pk_bf16_f32 v154, v154, v157
	v_cvt_pk_bf16_f32 v155, v155, v156
	v_cvt_pk_bf16_f32 v156, v224, v225
	v_cvt_pk_bf16_f32 v157, v226, v227
	v_cvt_pk_bf16_f32 v158, v228, v217
	v_cvt_pk_bf16_f32 v159, v218, v219
	v_cvt_pk_bf16_f32 v160, v220, v221
	v_cvt_pk_bf16_f32 v161, v222, v223
	v_cvt_pk_bf16_f32 v162, v231, v229
	v_cvt_pk_bf16_f32 v163, v230, v232
	s_nop 1
	v_permlane32_swap_b32_e32 v215, v216
	v_permlane32_swap_b32_e32 v148, v150
	v_permlane32_swap_b32_e32 v149, v151
	v_permlane32_swap_b32_e32 v152, v154
	v_permlane32_swap_b32_e32 v153, v155
	v_permlane32_swap_b32_e32 v156, v158
	v_permlane32_swap_b32_e32 v157, v159
	v_permlane32_swap_b32_e32 v160, v162
	v_permlane32_swap_b32_e32 v161, v163
	s_add_i32 s0, s74, 1
	s_cmp_lt_i32 s0, s75
	s_cselect_b64 s[36:37], -1, 0
	s_cmp_ge_i32 s0, s75
	s_cbranch_scc1 .LBB0_979
	v_add_co_u32_e32 v128, vcc, 0xc0000, v180
	s_nop 1
	v_addc_co_u32_e32 v129, vcc, 0, v181, vcc
	v_add_co_u32_e32 v132, vcc, 0xe0000, v180
	s_nop 1
	v_addc_co_u32_e32 v133, vcc, 0, v181, vcc
	v_add_co_u32_e32 v136, vcc, 0xc0000, v178
	s_nop 1
	v_addc_co_u32_e32 v137, vcc, 0, v179, vcc
	v_add_co_u32_e32 v140, vcc, 0xe0000, v178
	s_nop 1
	v_addc_co_u32_e32 v141, vcc, 0, v179, vcc
	v_add_co_u32_e32 v144, vcc, 0x2000, v176
	s_nop 1
	v_addc_co_u32_e32 v145, vcc, 0, v177, vcc
	global_load_dwordx4 v[136:139], v[136:137], off
	global_load_dwordx4 v[140:143], v[140:141], off
	global_load_dwordx4 v[144:147], v[144:145], off
	global_load_dwordx4 v[128:131], v[128:129], off
	global_load_dwordx4 v[132:135], v[132:133], off
; template <int VB>
; __device__ __forceinline__ void pv_tile(f32x16* o, int vb0, bf16x8 pa0, bf16x8 pa1, bf16x8 pa2, bf16x8 pa3) {
;     ...
;     PV_D2(0, 1); PV_D2(2, 3);
.LBB0_979:
	ds_read_b64_tr_b16 v[178:179], v188 offset:0x4000
	ds_read_b64_tr_b16 v[180:181], v188 offset:0x4800
	ds_read_b64_tr_b16 v[218:219], v188 offset:0x4200
	ds_read_b64_tr_b16 v[220:221], v188 offset:0x4a00
	ds_read_b64_tr_b16 v[222:223], v188 offset:0x5000
	ds_read_b64_tr_b16 v[224:225], v188 offset:0x5800
	ds_read_b64_tr_b16 v[226:227], v188 offset:0x5200
	ds_read_b64_tr_b16 v[228:229], v188 offset:0x5a00
	ds_read_b64_tr_b16 v[230:231], v188 offset:0x6000
	ds_read_b64_tr_b16 v[232:233], v188 offset:0x6800
	ds_read_b64_tr_b16 v[234:235], v188 offset:0x6200
	ds_read_b64_tr_b16 v[236:237], v188 offset:0x6a00
	ds_read_b64_tr_b16 v[238:239], v188 offset:0x7000
	ds_read_b64_tr_b16 v[240:241], v188 offset:0x7800
	ds_read_b64_tr_b16 v[242:243], v188 offset:0x7200
	ds_read_b64_tr_b16 v[244:245], v188 offset:0x7a00
	s_waitcnt lgkmcnt(14)
	s_nop 0
	v_mfma_f32_32x32x16_bf16 v[48:63], v[148:151], v[178:181], v[48:63]
	ds_read_b64_tr_b16 v[178:179], v188 offset:0x4400
	ds_read_b64_tr_b16 v[180:181], v188 offset:0x4c00
	s_waitcnt lgkmcnt(14)
	v_mfma_f32_32x32x16_bf16 v[32:47], v[148:151], v[218:221], v[32:47]
	ds_read_b64_tr_b16 v[218:219], v188 offset:0x4600
	ds_read_b64_tr_b16 v[220:221], v188 offset:0x4e00
	s_waitcnt lgkmcnt(14)
	v_mfma_f32_32x32x16_bf16 v[48:63], v[152:155], v[222:225], v[48:63]
	ds_read_b64_tr_b16 v[222:223], v188 offset:0x5400
	ds_read_b64_tr_b16 v[224:225], v188 offset:0x5c00
	s_waitcnt lgkmcnt(14)
	v_mfma_f32_32x32x16_bf16 v[32:47], v[152:155], v[226:229], v[32:47]
	ds_read_b64_tr_b16 v[226:227], v188 offset:0x5600
	ds_read_b64_tr_b16 v[228:229], v188 offset:0x5e00
	s_waitcnt lgkmcnt(14)
	v_mfma_f32_32x32x16_bf16 v[48:63], v[156:159], v[230:233], v[48:63]
	ds_read_b64_tr_b16 v[230:231], v188 offset:0x6400
	ds_read_b64_tr_b16 v[232:233], v188 offset:0x6c00
	s_waitcnt lgkmcnt(14)
	v_mfma_f32_32x32x16_bf16 v[32:47], v[156:159], v[234:237], v[32:47]
	ds_read_b64_tr_b16 v[234:235], v188 offset:0x6600
	ds_read_b64_tr_b16 v[236:237], v188 offset:0x6e00
	s_waitcnt lgkmcnt(14)
	v_mfma_f32_32x32x16_bf16 v[48:63], v[160:163], v[238:241], v[48:63]
	ds_read_b64_tr_b16 v[238:239], v188 offset:0x7400
	ds_read_b64_tr_b16 v[240:241], v188 offset:0x7c00
	s_waitcnt lgkmcnt(14)
	v_mfma_f32_32x32x16_bf16 v[32:47], v[160:163], v[242:245], v[32:47]
	ds_read_b64_tr_b16 v[246:247], v188 offset:0x7600
	ds_read_b64_tr_b16 v[248:249], v188 offset:0x7e00
	s_waitcnt lgkmcnt(14)
	v_mfma_f32_32x32x16_bf16 v[16:31], v[148:151], v[178:181], v[16:31]
	s_cmp_le_i32 s68, s95
	s_waitcnt lgkmcnt(12)
	v_mfma_f32_32x32x16_bf16 v[0:15], v[148:151], v[218:221], v[0:15]
	s_waitcnt lgkmcnt(10)
	v_mfma_f32_32x32x16_bf16 v[16:31], v[152:155], v[222:225], v[16:31]
	s_waitcnt lgkmcnt(8)
	v_mfma_f32_32x32x16_bf16 v[0:15], v[152:155], v[226:229], v[0:15]
	s_waitcnt lgkmcnt(6)
	v_mfma_f32_32x32x16_bf16 v[16:31], v[156:159], v[230:233], v[16:31]
	s_waitcnt lgkmcnt(4)
	v_mfma_f32_32x32x16_bf16 v[0:15], v[156:159], v[234:237], v[0:15]
	s_waitcnt lgkmcnt(2)
	v_mfma_f32_32x32x16_bf16 v[16:31], v[160:163], v[238:241], v[16:31]
	s_waitcnt lgkmcnt(0)
	v_mfma_f32_32x32x16_bf16 v[0:15], v[160:163], v[246:249], v[0:15]
	s_mov_b64 vcc, s[36:37]
	s_cbranch_vccz .Lattn_kw2_skip
	s_waitcnt vmcnt(2)
	ds_write_b128 v169, v[136:139] offset:24576
	ds_write_b128 v169, v[140:143] offset:36864
	ds_write_b128 v182, v[144:147] offset:24576
; __device__ __forceinline__ void mask_tile(f32x16& p0, f32x16& p1, int dq) {
;     const float NEG = -__builtin_inff();
; #pragma unroll
;     for (int r = 0; r < 16; ++r) { const int c = (r & 3) + 8 * (r >> 2); if (dq - c < 0) p0[r] = NEG; if (dq - c - 32 < 0) p1[r] = NEG; }
; }
; __device__ __forceinline__ void partialSM(f32x16& p0, f32x16& p1, float& m_reg, float& mn, float& alpha) {
;     float pmax = p0[0];
; #pragma unroll
;     for (int r = 1; r < 16; ++r) pmax = fmaxf(pmax, p0[r]);
; #pragma unroll
;     for (int r = 0; r < 16; ++r) pmax = fmaxf(pmax, p1[r]);
;     { auto rr = __builtin_amdgcn_permlane32_swap(__float_as_uint(pmax), __float_as_uint(pmax), false, false);
;       pmax = fmaxf(__uint_as_float(rr[0]), __uint_as_float(rr[1])); }
;     constexpr float C2 = 1.4426950408889634f * SCALE;
;     if (__builtin_expect(__all((pmax - m_reg) * SCALE <= THR), 1)) { mn = m_reg; alpha = 1.f; }
;     else { mn = fmaxf(m_reg, pmax); alpha = __builtin_amdgcn_exp2f((m_reg - mn) * C2); m_reg = mn; }
;     const float mnL = -mn * C2;
; #pragma unroll
;     for (int r = 0; r < 16; ++r) p0[r] = fmaf(p0[r], C2, mnL);
; #pragma unroll
;     for (int r = 0; r < 16; ++r) p1[r] = fmaf(p1[r], C2, mnL);
; #pragma unroll
;     for (int r = 0; r < 16; ++r) p0[r] = __builtin_amdgcn_exp2f(p0[r]);
; }
.Lattn_kw2_skip:
	s_cbranch_scc1 .LBB0_981
	v_cmp_gt_i32_e64 s[64:65], 26, v210
	v_cmp_gt_i32_e64 s[66:67], 27, v210
	v_cmp_gt_i32_e64 s[62:63], 25, v210
	s_and_b64 s[64:65], s[66:67], s[64:65]
	v_cmp_gt_i32_e64 s[60:61], 24, v210
	s_and_b64 s[62:63], s[64:65], s[62:63]
	v_cmp_gt_i32_e64 s[58:59], 19, v210
	s_and_b64 s[60:61], s[62:63], s[60:61]
	v_cmp_gt_i32_e64 s[56:57], 18, v210
	s_and_b64 s[58:59], s[60:61], s[58:59]
	v_cmp_gt_i32_e64 s[54:55], 17, v210
	s_and_b64 s[56:57], s[58:59], s[56:57]
	v_cmp_gt_i32_e64 s[52:53], 16, v210
	s_and_b64 s[54:55], s[56:57], s[54:55]
	v_cmp_gt_i32_e64 s[50:51], 11, v210
	s_and_b64 s[52:53], s[54:55], s[52:53]
	v_cmp_gt_i32_e64 s[48:49], 10, v210
	s_and_b64 s[50:51], s[52:53], s[50:51]
	v_cmp_gt_i32_e64 s[46:47], 9, v210
	s_and_b64 s[48:49], s[50:51], s[48:49]
	v_cmp_gt_i32_e64 s[44:45], 8, v210
	s_and_b64 s[46:47], s[48:49], s[46:47]
	v_cmp_gt_i32_e64 s[42:43], 3, v210
	s_and_b64 s[44:45], s[46:47], s[44:45]
	v_cmp_gt_i32_e64 s[40:41], 2, v210
	s_and_b64 s[42:43], s[44:45], s[42:43]
	v_cmp_gt_i32_e64 s[38:39], 1, v210
	s_and_b64 s[40:41], s[42:43], s[40:41]
	v_cmp_gt_i32_e64 s[34:35], 0, v210
	s_and_b64 s[38:39], s[40:41], s[38:39]
	s_and_b64 s[34:35], s[38:39], s[34:35]
	v_cmp_gt_i32_e64 s[30:31], 58, v210
	v_cndmask_b32_e64 v80, v80, v198, s[34:35]
	v_cmp_gt_i32_e64 s[34:35], 59, v210
	v_cmp_gt_i32_e64 s[28:29], 57, v210
	s_and_b64 s[30:31], s[34:35], s[30:31]
	v_cmp_gt_i32_e64 s[26:27], 56, v210
	s_and_b64 s[28:29], s[30:31], s[28:29]
	v_cmp_gt_i32_e64 s[24:25], 51, v210
	s_and_b64 s[26:27], s[28:29], s[26:27]
	v_cmp_gt_i32_e64 s[22:23], 50, v210
	s_and_b64 s[24:25], s[26:27], s[24:25]
	v_cmp_gt_i32_e64 s[20:21], 49, v210
	s_and_b64 s[22:23], s[24:25], s[22:23]
	v_cmp_gt_i32_e64 s[18:19], 48, v210
	s_and_b64 s[20:21], s[22:23], s[20:21]
	v_cmp_gt_i32_e64 s[16:17], 43, v210
	s_and_b64 s[18:19], s[20:21], s[18:19]
	v_cmp_gt_i32_e64 s[14:15], 42, v210
	s_and_b64 s[16:17], s[18:19], s[16:17]
	v_cmp_gt_i32_e64 s[12:13], 41, v210
	s_and_b64 s[14:15], s[16:17], s[14:15]
	v_cmp_gt_i32_e64 s[10:11], 40, v210
	s_and_b64 s[12:13], s[14:15], s[12:13]
	v_cmp_gt_i32_e64 s[8:9], 35, v210
	s_and_b64 s[10:11], s[12:13], s[10:11]
	v_cmp_gt_i32_e64 s[6:7], 34, v210
	s_and_b64 s[8:9], s[10:11], s[8:9]
	v_cmp_gt_i32_e64 s[0:1], 33, v210
	s_and_b64 s[6:7], s[8:9], s[6:7]
	v_cmp_gt_i32_e32 vcc, 32, v210
	s_and_b64 s[0:1], s[6:7], s[0:1]
	s_and_b64 vcc, s[0:1], vcc
	v_cndmask_b32_e64 v95, v95, v198, s[66:67]
	v_cndmask_b32_e64 v94, v94, v198, s[64:65]
	v_cndmask_b32_e64 v93, v93, v198, s[62:63]
	v_cndmask_b32_e64 v92, v92, v198, s[60:61]
	v_cndmask_b32_e64 v91, v91, v198, s[58:59]
	v_cndmask_b32_e64 v90, v90, v198, s[56:57]
	v_cndmask_b32_e64 v89, v89, v198, s[54:55]
	v_cndmask_b32_e64 v88, v88, v198, s[52:53]
	v_cndmask_b32_e64 v87, v87, v198, s[50:51]
	v_cndmask_b32_e64 v86, v86, v198, s[48:49]
	v_cndmask_b32_e64 v85, v85, v198, s[46:47]
	v_cndmask_b32_e64 v84, v84, v198, s[44:45]
	v_cndmask_b32_e64 v83, v83, v198, s[42:43]
	v_cndmask_b32_e64 v82, v82, v198, s[40:41]
	v_cndmask_b32_e64 v81, v81, v198, s[38:39]
	v_cndmask_b32_e64 v79, v79, v198, s[34:35]
	v_cndmask_b32_e64 v78, v78, v198, s[30:31]
	v_cndmask_b32_e64 v77, v77, v198, s[28:29]
	v_cndmask_b32_e64 v76, v76, v198, s[26:27]
	v_cndmask_b32_e64 v75, v75, v198, s[24:25]
	v_cndmask_b32_e64 v74, v74, v198, s[22:23]
	v_cndmask_b32_e64 v73, v73, v198, s[20:21]
	v_cndmask_b32_e64 v72, v72, v198, s[18:19]
	v_cndmask_b32_e64 v71, v71, v198, s[16:17]
	v_cndmask_b32_e64 v70, v70, v198, s[14:15]
	v_cndmask_b32_e64 v69, v69, v198, s[12:13]
	v_cndmask_b32_e64 v68, v68, v198, s[10:11]
	v_cndmask_b32_e64 v67, v67, v198, s[8:9]
	v_cndmask_b32_e64 v66, v66, v198, s[6:7]
	v_cndmask_b32_e64 v65, v65, v198, s[0:1]
	v_cndmask_b32_e32 v64, v64, v198, vcc
.LBB0_981:
	v_max_f32_e32 v148, v81, v81
	v_max_f32_e32 v149, v80, v80
	v_max_f32_e32 v148, v149, v148
	v_max3_f32 v148, v148, v82, v83
	v_max3_f32 v148, v148, v84, v85
	v_max3_f32 v148, v148, v86, v87
	v_max3_f32 v148, v148, v88, v89
	v_max3_f32 v148, v148, v90, v91
	v_max3_f32 v148, v148, v92, v93
	v_max3_f32 v148, v148, v94, v95
	v_max3_f32 v148, v148, v64, v65
	v_max3_f32 v148, v148, v66, v67
	v_max3_f32 v148, v148, v68, v69
	v_max3_f32 v148, v148, v70, v71
	v_max3_f32 v148, v148, v72, v73
	v_max3_f32 v148, v148, v74, v75
	v_max3_f32 v148, v148, v76, v77
	v_max3_f32 v148, v148, v78, v79
	v_mov_b32_e32 v149, v148
	s_nop 1
	v_permlane32_swap_b32_e32 v148, v149
	v_max_f32_e32 v149, v149, v149
	v_max_f32_e32 v148, v148, v148
	v_max_f32_e32 v148, v148, v149
	v_sub_f32_e32 v149, v148, v214
	v_mul_f32_e32 v149, 0x3d93cd3a, v149
	v_cmp_ge_f32_e32 vcc, s33, v149
	s_cmp_eq_u64 vcc, exec
	s_cselect_b64 s[6:7], -1, 0
	s_andn2_b64 vcc, exec, s[36:37]
	s_barrier
	s_cbranch_vccnz .LBB0_983
	s_waitcnt vmcnt(0)
	ds_write_b128 v207, v[128:131]
	ds_write_b128 v208, v[132:135]

; #define SBAR() __builtin_amdgcn_sched_barrier(0)
; __device__ __forceinline__ void finishSM(f32x16& p0, f32x16& p1, float alpha, float& l_reg, bf16x8& pa0, bf16x8& pa1, bf16x8& pa2, bf16x8& pa3) {
; #pragma unroll
;     for (int r = 0; r < 16; ++r) p1[r] = __builtin_amdgcn_exp2f(p1[r]);
;     float ps = 0;
; #pragma unroll
;     for (int r = 0; r < 16; ++r) ps += p0[r];
; #pragma unroll
;     for (int r = 0; r < 16; ++r) ps += p1[r];
;     { auto rr = __builtin_amdgcn_permlane32_swap(__float_as_uint(ps), __float_as_uint(ps), false, false);
;       ps = __uint_as_float(rr[0]) + __uint_as_float(rr[1]); }
;     l_reg = l_reg * alpha + ps;
;     PK4(p0, 0, pa0); PK4(p0, 8, pa1); PK4(p1, 0, pa2); PK4(p1, 8, pa3);
; }
; template <int KB>
; __device__ __forceinline__ void qkt(f32x16& p0, f32x16& p1, const char* K_lds, int r32, int hi, const bf16x8* qr, const char* qx) {
;     p0 = f32x16{}; p1 = f32x16{};
;     const char* kb[4];
; #pragma unroll
;     for (int dd = 0; dd < 4; ++dd) kb[dd] = K_lds + KB * SHM_K + KSWZ(r32, (dd * 16 + hi * 8) * 2);
; #pragma unroll
;     for (int d0 = 0; d0 < 12; ++d0) { const char* a = kb[d0 & 3] + (d0 >> 2) * 128;
;         bf16x8 b0 = *reinterpret_cast<const bf16x8*>(a);
;         bf16x8 b1 = *reinterpret_cast<const bf16x8*>(a + 32 * 384);
;         const bf16x8 q = d0 < 8 ? qr[d0 & 7] : *reinterpret_cast<const bf16x8*>(qx + (d0 - 8) * 1024);
;         p0 = __builtin_amdgcn_mfma_f32_32x32x16_bf16(b0, q, p0, 0, 0, 0);
;         p1 = __builtin_amdgcn_mfma_f32_32x32x16_bf16(b1, q, p1, 0, 0, 0); }
; }
; __device__ __forceinline__ void attn_block(const BlockRef& cur, const BlockRef& nxt, char* lds, Seam& S) {
;     ...
;     SBAR(); qkt<1>(pB0, pB1, K_lds, r32, hi, S.qr, qx); SBAR();
;     finishSM(pA0, pA1, alA, l_reg, pa0, pa1, pa2, pa3); SBAR();
;     pv_tile<0>(o, vb0, pa0, pa1, pa2, pa3);
.LBB0_991:
	s_setprio 0
	v_readlane_b32 s68, v254, 55
	ds_read_b128 v[64:67], v194 offset:24576
	ds_read_b128 v[176:179], v194 offset:37120
	s_waitcnt lgkmcnt(1)
	v_mfma_f32_32x32x16_bf16 v[80:95], v[64:67], v[124:127], 0
	ds_read_b128 v[64:67], v194 offset:36864
	ds_read_b128 v[206:209], v194 offset:36992
	s_waitcnt lgkmcnt(1)
	v_mfma_f32_32x32x16_bf16 v[64:79], v[64:67], v[124:127], 0
	ds_read_b128 v[124:127], v195 offset:24576
	ds_read_b128 v[210:213], v195 offset:37120
	s_waitcnt lgkmcnt(1)
	v_mfma_f32_32x32x16_bf16 v[80:95], v[124:127], v[120:123], v[80:95]
	ds_read_b128 v[124:127], v195 offset:36864
	ds_read_b128 v[214:217], v195 offset:36992
	s_waitcnt lgkmcnt(1)
	v_mfma_f32_32x32x16_bf16 v[64:79], v[124:127], v[120:123], v[64:79]
	ds_read_b128 v[120:123], v196 offset:24576
	ds_read_b128 v[124:127], v196 offset:37120
	s_waitcnt lgkmcnt(1)
	v_mfma_f32_32x32x16_bf16 v[80:95], v[120:123], v[116:119], v[80:95]
	ds_read_b128 v[120:123], v196 offset:36864
	ds_read_b128 v[218:221], v196 offset:36992
	s_waitcnt lgkmcnt(1)
	v_mfma_f32_32x32x16_bf16 v[64:79], v[120:123], v[116:119], v[64:79]
	ds_read_b128 v[116:119], v197 offset:24576
	ds_read_b128 v[120:123], v197 offset:37120
	s_waitcnt lgkmcnt(1)
	v_mfma_f32_32x32x16_bf16 v[80:95], v[116:119], v[112:115], v[80:95]
	ds_read_b128 v[116:119], v197 offset:36864
	ds_read_b128 v[222:225], v197 offset:36992
	s_waitcnt lgkmcnt(1)
	v_mfma_f32_32x32x16_bf16 v[64:79], v[116:119], v[112:115], v[64:79]
	ds_read_b128 v[112:115], v194 offset:24704
	ds_read_b128 v[116:119], v194 offset:24832
	s_waitcnt lgkmcnt(1)
	v_mfma_f32_32x32x16_bf16 v[80:95], v[112:115], v[108:111], v[80:95]
	v_mfma_f32_32x32x16_bf16 v[64:79], v[206:209], v[108:111], v[64:79]
	ds_read_b128 v[108:111], v195 offset:24704
	ds_read_b128 v[112:115], v195 offset:24832
	s_waitcnt lgkmcnt(1)
	v_mfma_f32_32x32x16_bf16 v[80:95], v[108:111], v[104:107], v[80:95]
	v_mfma_f32_32x32x16_bf16 v[64:79], v[214:217], v[104:107], v[64:79]
	ds_read_b128 v[104:107], v196 offset:24704
	ds_read_b128 v[108:111], v196 offset:24832
	s_waitcnt lgkmcnt(1)
	v_mfma_f32_32x32x16_bf16 v[80:95], v[104:107], v[100:103], v[80:95]
	v_mfma_f32_32x32x16_bf16 v[64:79], v[218:221], v[100:103], v[64:79]
	ds_read_b128 v[100:103], v197 offset:24704
	ds_read_b128 v[104:107], v197 offset:24832
	s_waitcnt lgkmcnt(1)
	v_mfma_f32_32x32x16_bf16 v[80:95], v[100:103], v[96:99], v[80:95]
	v_mfma_f32_32x32x16_bf16 v[64:79], v[222:225], v[96:99], v[64:79]
	ds_read_b128 v[96:99], v204
	ds_read_b128 v[100:103], v204 offset:1024
	s_waitcnt lgkmcnt(1)
	v_mfma_f32_32x32x16_bf16 v[80:95], v[116:119], v[96:99], v[80:95]
	v_mfma_f32_32x32x16_bf16 v[64:79], v[176:179], v[96:99], v[64:79]
	s_waitcnt lgkmcnt(0)
	v_mfma_f32_32x32x16_bf16 v[80:95], v[112:115], v[100:103], v[80:95]
	v_mfma_f32_32x32x16_bf16 v[64:79], v[210:213], v[100:103], v[64:79]
	ds_read_b128 v[96:99], v204 offset:2048
	ds_read_b128 v[100:103], v204 offset:3072
	s_waitcnt lgkmcnt(1)
	v_mfma_f32_32x32x16_bf16 v[80:95], v[108:111], v[96:99], v[80:95]
	v_mfma_f32_32x32x16_bf16 v[64:79], v[124:127], v[96:99], v[64:79]
	s_waitcnt lgkmcnt(0)
	v_mfma_f32_32x32x16_bf16 v[80:95], v[104:107], v[100:103], v[80:95]
	v_mfma_f32_32x32x16_bf16 v[64:79], v[120:123], v[100:103], v[64:79]
	v_add_f32_e32 v96, 0, v159
	v_add_f32_e32 v96, v161, v96
	v_add_f32_e32 v96, v157, v96
	v_add_f32_e32 v96, v160, v96
	v_add_f32_e32 v96, v156, v96
	v_add_f32_e32 v96, v158, v96
	v_add_f32_e32 v96, v154, v96
	v_add_f32_e32 v96, v155, v96
	v_add_f32_e32 v96, v150, v96
	v_add_f32_e32 v96, v153, v96
	v_add_f32_e32 v96, v146, v96
	v_add_f32_e32 v96, v151, v96
	v_exp_f32_e32 v104, v142
	v_add_f32_e32 v96, v144, v96
	v_exp_f32_e32 v105, v143
	v_add_f32_e32 v96, v152, v96
	v_exp_f32_e32 v106, v140
	v_add_f32_e32 v96, v145, v96
	v_exp_f32_e32 v107, v141
	v_add_f32_e32 v96, v147, v96
	v_exp_f32_e32 v108, v138
	v_add_f32_e32 v96, v104, v96
	v_exp_f32_e32 v109, v139
	v_add_f32_e32 v96, v105, v96
	v_exp_f32_e32 v110, v136
	v_add_f32_e32 v96, v106, v96
	v_exp_f32_e32 v111, v137
	v_add_f32_e32 v96, v107, v96
	v_exp_f32_e32 v112, v134
	v_add_f32_e32 v96, v108, v96
	v_exp_f32_e32 v113, v135
	v_add_f32_e32 v96, v109, v96
	v_exp_f32_e32 v114, v132
	v_add_f32_e32 v96, v110, v96
	v_exp_f32_e32 v115, v133
	v_add_f32_e32 v96, v111, v96
	v_exp_f32_e32 v116, v130
	v_add_f32_e32 v96, v112, v96
	v_exp_f32_e32 v117, v131
	v_add_f32_e32 v96, v113, v96
	v_exp_f32_e32 v118, v128
	v_add_f32_e32 v96, v114, v96
	v_exp_f32_e32 v119, v129
	v_add_f32_e32 v96, v115, v96
	v_add_f32_e32 v96, v116, v96
	v_add_f32_e32 v96, v117, v96
	v_add_f32_e32 v96, v118, v96
	v_add_f32_e32 v162, v119, v96
	v_mov_b32_e32 v163, v162
	s_nop 1
	v_permlane32_swap_b32_e32 v162, v163
	v_cvt_pk_bf16_f32 v96, v159, v161
	v_cvt_pk_bf16_f32 v97, v157, v160
	v_cvt_pk_bf16_f32 v98, v156, v158
	v_cvt_pk_bf16_f32 v99, v154, v155
	v_cvt_pk_bf16_f32 v100, v150, v153
	v_cvt_pk_bf16_f32 v101, v146, v151
	v_cvt_pk_bf16_f32 v102, v144, v152
	v_cvt_pk_bf16_f32 v103, v145, v147
	v_cvt_pk_bf16_f32 v104, v104, v105
	v_cvt_pk_bf16_f32 v105, v106, v107
	v_cvt_pk_bf16_f32 v106, v108, v109
	v_cvt_pk_bf16_f32 v107, v110, v111
	v_cvt_pk_bf16_f32 v108, v112, v113
	v_cvt_pk_bf16_f32 v109, v114, v115
	v_cvt_pk_bf16_f32 v110, v116, v117
	v_cvt_pk_bf16_f32 v111, v118, v119
	s_nop 0
	v_permlane32_swap_b32_e32 v96, v98
	v_permlane32_swap_b32_e32 v97, v99
	v_permlane32_swap_b32_e32 v100, v102
	v_permlane32_swap_b32_e32 v101, v103
	v_permlane32_swap_b32_e32 v104, v106
	v_permlane32_swap_b32_e32 v105, v107
	v_permlane32_swap_b32_e32 v108, v110
	v_permlane32_swap_b32_e32 v109, v111
	ds_read_b64_tr_b16 v[112:113], v188 offset:0
	ds_read_b64_tr_b16 v[114:115], v188 offset:0x800
	ds_read_b64_tr_b16 v[116:117], v188 offset:0x200
	ds_read_b64_tr_b16 v[118:119], v188 offset:0xa00
	ds_read_b64_tr_b16 v[120:121], v188 offset:0x1000
	ds_read_b64_tr_b16 v[122:123], v188 offset:0x1800
	ds_read_b64_tr_b16 v[124:125], v188 offset:0x1200
	ds_read_b64_tr_b16 v[126:127], v188 offset:0x1a00
	ds_read_b64_tr_b16 v[128:129], v188 offset:0x2000
	ds_read_b64_tr_b16 v[130:131], v188 offset:0x2800
	ds_read_b64_tr_b16 v[132:133], v188 offset:0x2200
	ds_read_b64_tr_b16 v[134:135], v188 offset:0x2a00
	ds_read_b64_tr_b16 v[136:137], v188 offset:0x3000
	ds_read_b64_tr_b16 v[138:139], v188 offset:0x3800
	ds_read_b64_tr_b16 v[140:141], v188 offset:0x3200
	ds_read_b64_tr_b16 v[142:143], v188 offset:0x3a00
	s_waitcnt lgkmcnt(0)
; #define SBAR() __builtin_amdgcn_sched_barrier(0)
; #define RESC(a) do { if (__any((a) < 1.f)) { if (hi == 0) al_l[r32] = (a); asm volatile("s_waitcnt lgkmcnt(0)" ::: "memory");              \
;                      _Pragma("unroll") for (int d_ = 0; d_ < 4; ++d_) _Pragma("unroll") for (int r = 0; r < 16; ++r) o[d_][r] *= al_l[crow(r, hi)]; } } while (0)
; #define MASKT(P0_, P1_, t) do { const int kb_ = KBASE(t); if (kb_ + KVBLK - 1 > qlo) mask_tile(P0_, P1_, qm - kb_); } while (0)
; template <int VB>
; __device__ __forceinline__ void pv_tile(f32x16* o, int vb0, bf16x8 pa0, bf16x8 pa1, bf16x8 pa2, bf16x8 pa3) {
;     ...
;     PV_D2(0, 1); PV_D2(2, 3);
; __device__ __forceinline__ void attn_block(const BlockRef& cur, const BlockRef& nxt, char* lds, Seam& S) {
;     ...
;     SBAR(); SLOAD_H(nxt, 0); SBAR();
;     MASKT(pB0, pB1, NT - 1); partialSM(pB0, pB1, m_reg, mnB, alB); __syncthreads(); RESC(alB);
	s_nop 0
	v_mfma_f32_32x32x16_bf16 v[48:63], v[96:99], v[112:115], v[48:63]
	ds_read_b64_tr_b16 v[112:113], v188 offset:0x400
	ds_read_b64_tr_b16 v[114:115], v188 offset:0xc00
	v_mfma_f32_32x32x16_bf16 v[32:47], v[96:99], v[116:119], v[32:47]
	ds_read_b64_tr_b16 v[116:117], v188 offset:0x600
	ds_read_b64_tr_b16 v[118:119], v188 offset:0xe00
	v_mfma_f32_32x32x16_bf16 v[48:63], v[100:103], v[120:123], v[48:63]
	ds_read_b64_tr_b16 v[120:121], v188 offset:0x1400
	ds_read_b64_tr_b16 v[122:123], v188 offset:0x1c00
	v_mfma_f32_32x32x16_bf16 v[32:47], v[100:103], v[124:127], v[32:47]
	ds_read_b64_tr_b16 v[124:125], v188 offset:0x1600
	ds_read_b64_tr_b16 v[126:127], v188 offset:0x1e00
	v_mfma_f32_32x32x16_bf16 v[48:63], v[104:107], v[128:131], v[48:63]
	ds_read_b64_tr_b16 v[128:129], v188 offset:0x2400
	ds_read_b64_tr_b16 v[130:131], v188 offset:0x2c00
	v_mfma_f32_32x32x16_bf16 v[32:47], v[104:107], v[132:135], v[32:47]
	ds_read_b64_tr_b16 v[132:133], v188 offset:0x2600
	ds_read_b64_tr_b16 v[134:135], v188 offset:0x2e00
	v_mfma_f32_32x32x16_bf16 v[48:63], v[108:111], v[136:139], v[48:63]
	ds_read_b64_tr_b16 v[136:137], v188 offset:0x3400
	ds_read_b64_tr_b16 v[138:139], v188 offset:0x3c00
	ds_read_b64_tr_b16 v[144:145], v188 offset:0x3600
	ds_read_b64_tr_b16 v[146:147], v188 offset:0x3e00
	s_waitcnt lgkmcnt(0)
	v_mfma_f32_32x32x16_bf16 v[32:47], v[108:111], v[140:143], v[32:47]
	v_mfma_f32_32x32x16_bf16 v[16:31], v[96:99], v[112:115], v[16:31]
	v_mfma_f32_32x32x16_bf16 v[0:15], v[96:99], v[116:119], v[0:15]
	v_mfma_f32_32x32x16_bf16 v[16:31], v[100:103], v[120:123], v[16:31]
	v_mfma_f32_32x32x16_bf16 v[0:15], v[100:103], v[124:127], v[0:15]
	v_mfma_f32_32x32x16_bf16 v[16:31], v[104:107], v[128:131], v[16:31]
	v_mfma_f32_32x32x16_bf16 v[0:15], v[104:107], v[132:135], v[0:15]
	v_mfma_f32_32x32x16_bf16 v[16:31], v[108:111], v[136:139], v[16:31]
	v_mfma_f32_32x32x16_bf16 v[0:15], v[108:111], v[144:147], v[0:15]
	v_lshl_add_u64 v[96:97], s[92:93], 0, v[164:165]
	s_mov_b32 s0, 0x20000
	v_add_co_u32_e32 v96, vcc, s0, v96
	s_nop 1
	v_addc_co_u32_e32 v97, vcc, 0, v97, vcc
	global_load_dwordx4 v[132:135], v[96:97], off
	v_lshl_add_u64 v[96:97], s[84:85], 0, v[164:165]
	v_add_co_u32_e32 v96, vcc, 0x20000, v96
	global_load_dwordx4 v[144:147], v164, s[92:93]
	global_load_dwordx4 v[128:131], v164, s[84:85]
	v_addc_co_u32_e32 v97, vcc, 0, v97, vcc
	global_load_dwordx4 v[136:139], v[96:97], off
	global_load_dwordx4 v[140:143], v174, s[72:73]
	s_cmpk_lt_u32 s94, 0x200
	s_cbranch_scc0 .LBB0_994
	v_subrev_u32_e32 v96, s1, v203
	v_add_u32_e32 v96, 64, v96
	v_cmp_gt_i32_e64 s[64:65], 26, v96
	v_cmp_gt_i32_e64 s[66:67], 27, v96
	v_cmp_gt_i32_e64 s[62:63], 25, v96
	s_and_b64 s[64:65], s[66:67], s[64:65]
	v_cmp_gt_i32_e64 s[60:61], 24, v96
	s_and_b64 s[62:63], s[64:65], s[62:63]
	v_cmp_gt_i32_e64 s[58:59], 19, v96
	s_and_b64 s[60:61], s[62:63], s[60:61]
	v_cmp_gt_i32_e64 s[56:57], 18, v96
	s_and_b64 s[58:59], s[60:61], s[58:59]
	v_cmp_gt_i32_e64 s[54:55], 17, v96
	s_and_b64 s[56:57], s[58:59], s[56:57]
	v_cmp_gt_i32_e64 s[52:53], 16, v96
	s_and_b64 s[54:55], s[56:57], s[54:55]
	v_cmp_gt_i32_e64 s[50:51], 11, v96
	s_and_b64 s[52:53], s[54:55], s[52:53]
	v_cmp_gt_i32_e64 s[48:49], 10, v96
	s_and_b64 s[50:51], s[52:53], s[50:51]
	v_cmp_gt_i32_e64 s[46:47], 9, v96
	s_and_b64 s[48:49], s[50:51], s[48:49]
	v_cmp_gt_i32_e64 s[44:45], 8, v96
	s_and_b64 s[46:47], s[48:49], s[46:47]
	v_cmp_gt_i32_e64 s[42:43], 3, v96
	s_and_b64 s[44:45], s[46:47], s[44:45]
	v_cmp_gt_i32_e64 s[40:41], 2, v96
	s_and_b64 s[42:43], s[44:45], s[42:43]
	v_cmp_gt_i32_e64 s[38:39], 1, v96
	s_and_b64 s[40:41], s[42:43], s[40:41]
	v_cmp_gt_i32_e64 s[34:35], 0, v96
	s_and_b64 s[38:39], s[40:41], s[38:39]
	s_and_b64 s[34:35], s[38:39], s[34:35]
	v_cmp_gt_i32_e64 s[30:31], 58, v96
	v_cndmask_b32_e64 v80, v80, v198, s[34:35]
	v_cmp_gt_i32_e64 s[34:35], 59, v96
	v_cmp_gt_i32_e64 s[28:29], 57, v96
	s_and_b64 s[30:31], s[34:35], s[30:31]
	v_cmp_gt_i32_e64 s[26:27], 56, v96
	s_and_b64 s[28:29], s[30:31], s[28:29]
	v_cmp_gt_i32_e64 s[24:25], 51, v96
	s_and_b64 s[26:27], s[28:29], s[26:27]
	v_cmp_gt_i32_e64 s[22:23], 50, v96
	s_and_b64 s[24:25], s[26:27], s[24:25]
	v_cmp_gt_i32_e64 s[20:21], 49, v96
	s_and_b64 s[22:23], s[24:25], s[22:23]
	v_cmp_gt_i32_e64 s[18:19], 48, v96
	s_and_b64 s[20:21], s[22:23], s[20:21]
	v_cmp_gt_i32_e64 s[16:17], 43, v96
	s_and_b64 s[18:19], s[20:21], s[18:19]
	v_cmp_gt_i32_e64 s[14:15], 42, v96
	s_and_b64 s[16:17], s[18:19], s[16:17]
	v_cmp_gt_i32_e64 s[12:13], 41, v96
	s_and_b64 s[14:15], s[16:17], s[14:15]
	v_cmp_gt_i32_e64 s[10:11], 40, v96
	s_and_b64 s[12:13], s[14:15], s[12:13]
	v_cmp_gt_i32_e64 s[8:9], 35, v96
	s_and_b64 s[10:11], s[12:13], s[10:11]
	v_cmp_gt_i32_e64 s[6:7], 34, v96
	s_and_b64 s[8:9], s[10:11], s[8:9]
	v_cmp_gt_i32_e64 s[0:1], 33, v96
	s_and_b64 s[6:7], s[8:9], s[6:7]
	v_cmp_gt_i32_e32 vcc, 32, v96
	s_and_b64 s[0:1], s[6:7], s[0:1]
	s_and_b64 vcc, s[0:1], vcc
	v_cndmask_b32_e64 v95, v95, v198, s[66:67]
	v_cndmask_b32_e64 v94, v94, v198, s[64:65]
	v_cndmask_b32_e64 v93, v93, v198, s[62:63]
	v_cndmask_b32_e64 v92, v92, v198, s[60:61]
	v_cndmask_b32_e64 v91, v91, v198, s[58:59]
	v_cndmask_b32_e64 v90, v90, v198, s[56:57]
	v_cndmask_b32_e64 v89, v89, v198, s[54:55]
	v_cndmask_b32_e64 v88, v88, v198, s[52:53]
	v_cndmask_b32_e64 v87, v87, v198, s[50:51]
	v_cndmask_b32_e64 v86, v86, v198, s[48:49]
	v_cndmask_b32_e64 v85, v85, v198, s[46:47]
	v_cndmask_b32_e64 v84, v84, v198, s[44:45]
	v_cndmask_b32_e64 v83, v83, v198, s[42:43]
	v_cndmask_b32_e64 v82, v82, v198, s[40:41]
	v_cndmask_b32_e64 v81, v81, v198, s[38:39]
	v_cndmask_b32_e64 v79, v79, v198, s[34:35]
	v_cndmask_b32_e64 v78, v78, v198, s[30:31]
	v_cndmask_b32_e64 v77, v77, v198, s[28:29]
	v_cndmask_b32_e64 v76, v76, v198, s[26:27]
	v_cndmask_b32_e64 v75, v75, v198, s[24:25]
	v_cndmask_b32_e64 v74, v74, v198, s[22:23]
	v_cndmask_b32_e64 v73, v73, v198, s[20:21]
	v_cndmask_b32_e64 v72, v72, v198, s[18:19]
	v_cndmask_b32_e64 v71, v71, v198, s[16:17]
	v_cndmask_b32_e64 v70, v70, v198, s[14:15]
	v_cndmask_b32_e64 v69, v69, v198, s[12:13]
	v_cndmask_b32_e64 v68, v68, v198, s[10:11]
	v_cndmask_b32_e64 v67, v67, v198, s[8:9]
	v_cndmask_b32_e64 v66, v66, v198, s[6:7]
	v_cndmask_b32_e64 v65, v65, v198, s[0:1]
	v_cndmask_b32_e32 v64, v64, v198, vcc
